# speedup vs baseline: 1.0432x; 1.0004x over previous
; #define G_STAGE(bufoff, gbase) do { _Pragma("unroll") for (int _i = 0; _i < 2; ++_i) \
;     __builtin_amdgcn_global_load_lds((const unsigned*)((const char*)(gbase) + voffA[_i]), (LAS unsigned*)(lds + (bufoff) + ldsw + _i * 8192), 16, 0, 0); } while (0)
; #define G_LDA(dst, b, h) do { _Pragma("unroll") for (int m = 0; m < 4; ++m) _Pragma("unroll") for (int k = 0; k < 2; ++k) dst[m][k] = *(const LAS bf16x8*)(lds + G_SA(b, h) + aoff + m * 2048 + k * 1024); } while (0)
; #define G_LDB(dst, b, h) do { _Pragma("unroll") for (int n = 0; n < 2; ++n) _Pragma("unroll") for (int k = 0; k < 2; ++k) dst[n][k] = *(const LAS bf16x8*)(lds + G_SB(b, h) + boff + n * 2048 + k * 1024); } while (0)
; #define G_MMA(ai, bj, At, Bt) do { __builtin_amdgcn_s_setprio(1); _Pragma("unroll") for (int m = 0; m < 4; ++m) _Pragma("unroll") for (int n = 0; n < 2; ++n) _Pragma("unroll") for (int k = 0; k < 2; ++k) \
;     acc[ai][bj][m][n] = __builtin_amdgcn_mfma_f32_16x16x32_bf16(Bt[n][k], At[m][k], acc[ai][bj][m][n], 0, 0, 0); __builtin_amdgcn_s_setprio(0); } while (0)
; #define G_WAIT_V(n) asm volatile("s_waitcnt vmcnt(" #n ")" ::: "memory")
; #define G_WAIT_L(n) asm volatile("s_waitcnt lgkmcnt(" #n ")" ::: "memory")
; #define G_BAR __builtin_amdgcn_s_barrier()
; #define G_SCHED __builtin_amdgcn_sched_barrier(0)
; template <int MODE>
; __device__ __forceinline__ void gemm_phase(const Params& p, int layer, char* lds_generic) {
;     ...
;     for (int t = 0; t < nt; t += 2) {
;       const bool last = (t == nt - 2);
;       const char* a1 = cA + (size_t)(t + 1) * kstep;
;       const char* a2 = last ? nA : cA + (size_t)(t + 2) * kstep; const char* b2 = last ? nB : cB + (size_t)(t + 2) * kstep;
;       const char* a3 = a2 + kstep; const char* b3 = b2 + kstep;
;       G_LDB(B0, 0, 0); G_SCHED; G_LDA(At, 0, 0); G_STAGE(G_SA(1, 1), a1 + hstep);
;       G_WAIT_L(8); G_BAR; G_WAIT_L(0); G_MMA(0, 0, At, B0); G_BAR; G_SCHED;
;       G_LDB(B1, 0, 1); G_STAGE(G_SB(0, 0), b2);
;       G_BAR; G_WAIT_L(0); G_MMA(0, 1, At, B1); G_BAR;
;       G_LDA(At, 0, 1); G_STAGE(G_SA(0, 0), a2);
;       G_BAR; G_WAIT_L(0); G_MMA(1, 0, At, B0); G_BAR; G_SCHED;
;       G_STAGE(G_SB(0, 1), b2 + hstep);
;       G_WAIT_V(6); G_BAR; G_MMA(1, 1, At, B1); G_BAR;
;       G_LDB(B0, 1, 0); G_SCHED; G_LDA(At, 1, 0); G_STAGE(G_SA(0, 1), a2 + hstep);
;       G_WAIT_L(8); G_BAR; G_WAIT_L(0); G_MMA(0, 0, At, B0); G_BAR; G_SCHED;
.LBB0_88:
	ds_read_b128 v[156:159], v139
	ds_read_b128 v[160:163], v140
	ds_read_b128 v[164:167], v141
	ds_read_b128 v[168:171], v142
	s_add_u32 s12, s78, 0xfff80080
	s_addc_u32 s13, s79, -1
	s_cmp_eq_u32 s9, 28
	s_cselect_b32 s87, s67, s13
	s_cselect_b32 s86, vcc_lo, s12
	s_cselect_b32 s75, s69, s8
	s_cselect_b32 s74, vcc_hi, s5
	s_mov_b32 m0, s33
	v_lshl_add_u64 v[134:135], s[78:79], 0, v[130:131]
	ds_read_b128 v[172:175], v137
	ds_read_b128 v[176:179], v137 offset:1024
	ds_read_b128 v[180:183], v137 offset:2048
	ds_read_b128 v[184:187], v137 offset:3072
	ds_read_b128 v[188:191], v137 offset:4096
	ds_read_b128 v[194:197], v137 offset:5120
	ds_read_b128 v[198:201], v137 offset:6144
	ds_read_b128 v[202:205], v137 offset:7168
	global_load_lds_dwordx4 v[134:135], off
	v_lshl_add_u64 v[134:135], s[78:79], 0, v[132:133]
	s_mov_b32 m0, s1
	s_nop 0
	global_load_lds_dwordx4 v[134:135], off
	s_waitcnt lgkmcnt(8)
	s_barrier
	s_waitcnt lgkmcnt(0)
	v_mfma_f32_16x16x32_bf16 v[124:127], v[156:159], v[172:175], v[124:127]
	v_mfma_f32_16x16x32_bf16 v[120:123], v[164:167], v[172:175], v[120:123]
	v_mfma_f32_16x16x32_bf16 v[116:119], v[156:159], v[180:183], v[116:119]
	v_mfma_f32_16x16x32_bf16 v[108:111], v[164:167], v[180:183], v[108:111]
	v_mfma_f32_16x16x32_bf16 v[100:103], v[156:159], v[188:191], v[100:103]
	v_mfma_f32_16x16x32_bf16 v[92:95], v[164:167], v[188:191], v[92:95]
	v_mfma_f32_16x16x32_bf16 v[84:87], v[156:159], v[198:201], v[84:87]
	v_mfma_f32_16x16x32_bf16 v[76:79], v[164:167], v[198:201], v[76:79]
	v_mfma_f32_16x16x32_bf16 v[124:127], v[160:163], v[176:179], v[124:127]
	v_mfma_f32_16x16x32_bf16 v[120:123], v[168:171], v[176:179], v[120:123]
	v_mfma_f32_16x16x32_bf16 v[116:119], v[160:163], v[184:187], v[116:119]
	v_mfma_f32_16x16x32_bf16 v[108:111], v[168:171], v[184:187], v[108:111]
	v_mfma_f32_16x16x32_bf16 v[100:103], v[160:163], v[194:197], v[100:103]
	v_mfma_f32_16x16x32_bf16 v[92:95], v[168:171], v[194:197], v[92:95]
	v_mfma_f32_16x16x32_bf16 v[84:87], v[160:163], v[202:205], v[84:87]
	v_mfma_f32_16x16x32_bf16 v[76:79], v[168:171], v[202:205], v[76:79]
	s_barrier
	s_mov_b32 m0, s34
	v_lshl_add_u64 v[134:135], s[74:75], 0, v[192:193]
	ds_read_b128 v[206:209], v143
	ds_read_b128 v[216:219], v144
	ds_read_b128 v[222:225], v145
	ds_read_b128 v[228:231], v146
	global_load_lds_dwordx4 v[134:135], off
	v_lshl_add_u64 v[210:211], s[74:75], 0, v[128:129]
	s_mov_b32 m0, s35
	s_nop 0
	global_load_lds_dwordx4 v[210:211], off
	s_barrier
	s_waitcnt lgkmcnt(0)
	v_mfma_f32_16x16x32_bf16 v[112:115], v[206:209], v[172:175], v[112:115]
	v_mfma_f32_16x16x32_bf16 v[104:107], v[222:225], v[172:175], v[104:107]
	v_mfma_f32_16x16x32_bf16 v[96:99], v[206:209], v[180:183], v[96:99]
	v_mfma_f32_16x16x32_bf16 v[88:91], v[222:225], v[180:183], v[88:91]
	v_mfma_f32_16x16x32_bf16 v[80:83], v[206:209], v[188:191], v[80:83]
	v_mfma_f32_16x16x32_bf16 v[72:75], v[222:225], v[188:191], v[72:75]
	v_mfma_f32_16x16x32_bf16 v[68:71], v[206:209], v[198:201], v[68:71]
	v_mfma_f32_16x16x32_bf16 v[64:67], v[222:225], v[198:201], v[64:67]
	v_mfma_f32_16x16x32_bf16 v[112:115], v[216:219], v[176:179], v[112:115]
	v_mfma_f32_16x16x32_bf16 v[104:107], v[228:231], v[176:179], v[104:107]
	v_mfma_f32_16x16x32_bf16 v[96:99], v[216:219], v[184:187], v[96:99]
	v_mfma_f32_16x16x32_bf16 v[88:91], v[228:231], v[184:187], v[88:91]
	v_mfma_f32_16x16x32_bf16 v[80:83], v[216:219], v[194:197], v[80:83]
	v_mfma_f32_16x16x32_bf16 v[72:75], v[228:231], v[194:197], v[72:75]
	v_mfma_f32_16x16x32_bf16 v[68:71], v[216:219], v[202:205], v[68:71]
	v_mfma_f32_16x16x32_bf16 v[64:67], v[228:231], v[202:205], v[64:67]
	s_mov_b32 m0, s62
	v_lshl_add_u64 v[232:233], s[86:87], 0, v[192:193]
	s_barrier
	ds_read_b128 v[172:175], v137 offset:16384
	ds_read_b128 v[176:179], v137 offset:17408
	ds_read_b128 v[180:183], v137 offset:18432
	ds_read_b128 v[184:187], v137 offset:19456
	ds_read_b128 v[188:191], v137 offset:20480
	ds_read_b128 v[194:197], v137 offset:21504
	ds_read_b128 v[198:201], v137 offset:22528
	ds_read_b128 v[202:205], v137 offset:23552
	global_load_lds_dwordx4 v[232:233], off
	v_lshl_add_u64 v[234:235], s[86:87], 0, v[128:129]
	s_mov_b32 m0, s60
	s_nop 0
	global_load_lds_dwordx4 v[234:235], off
	s_barrier
	s_waitcnt lgkmcnt(0)
	v_mfma_f32_16x16x32_bf16 v[60:63], v[156:159], v[172:175], v[60:63]
	v_mfma_f32_16x16x32_bf16 v[56:59], v[164:167], v[172:175], v[56:59]
	v_mfma_f32_16x16x32_bf16 v[52:55], v[156:159], v[180:183], v[52:55]
	v_mfma_f32_16x16x32_bf16 v[44:47], v[164:167], v[180:183], v[44:47]
	v_mfma_f32_16x16x32_bf16 v[36:39], v[156:159], v[188:191], v[36:39]
	v_mfma_f32_16x16x32_bf16 v[28:31], v[164:167], v[188:191], v[28:31]
	v_mfma_f32_16x16x32_bf16 v[20:23], v[156:159], v[198:201], v[20:23]
	v_mfma_f32_16x16x32_bf16 v[12:15], v[164:167], v[198:201], v[12:15]
	v_mfma_f32_16x16x32_bf16 v[60:63], v[160:163], v[176:179], v[60:63]
	v_mfma_f32_16x16x32_bf16 v[56:59], v[168:171], v[176:179], v[56:59]
	v_mfma_f32_16x16x32_bf16 v[52:55], v[160:163], v[184:187], v[52:55]
	v_mfma_f32_16x16x32_bf16 v[44:47], v[168:171], v[184:187], v[44:47]
	v_mfma_f32_16x16x32_bf16 v[36:39], v[160:163], v[194:197], v[36:39]
	v_mfma_f32_16x16x32_bf16 v[28:31], v[168:171], v[194:197], v[28:31]
	v_mfma_f32_16x16x32_bf16 v[20:23], v[160:163], v[202:205], v[20:23]
	v_mfma_f32_16x16x32_bf16 v[12:15], v[168:171], v[202:205], v[12:15]
	s_barrier
	s_add_u32 s12, s74, 0x80000
	s_addc_u32 s13, s75, 0
	s_mov_b32 m0, s80
	v_lshl_add_u64 v[156:157], s[12:13], 0, v[192:193]
	global_load_lds_dwordx4 v[156:157], off
	v_lshl_add_u64 v[156:157], s[12:13], 0, v[128:129]
	s_mov_b32 m0, s82
	s_nop 0
	global_load_lds_dwordx4 v[156:157], off
	s_waitcnt vmcnt(6)
	s_barrier
; #define G_STAGE(bufoff, gbase) do { _Pragma("unroll") for (int _i = 0; _i < 2; ++_i) \
;     __builtin_amdgcn_global_load_lds((const unsigned*)((const char*)(gbase) + voffA[_i]), (LAS unsigned*)(lds + (bufoff) + ldsw + _i * 8192), 16, 0, 0); } while (0)
; #define G_LDA(dst, b, h) do { _Pragma("unroll") for (int m = 0; m < 4; ++m) _Pragma("unroll") for (int k = 0; k < 2; ++k) dst[m][k] = *(const LAS bf16x8*)(lds + G_SA(b, h) + aoff + m * 2048 + k * 1024); } while (0)
; #define G_LDB(dst, b, h) do { _Pragma("unroll") for (int n = 0; n < 2; ++n) _Pragma("unroll") for (int k = 0; k < 2; ++k) dst[n][k] = *(const LAS bf16x8*)(lds + G_SB(b, h) + boff + n * 2048 + k * 1024); } while (0)
; #define G_MMA(ai, bj, At, Bt) do { __builtin_amdgcn_s_setprio(1); _Pragma("unroll") for (int m = 0; m < 4; ++m) _Pragma("unroll") for (int n = 0; n < 2; ++n) _Pragma("unroll") for (int k = 0; k < 2; ++k) \
;     acc[ai][bj][m][n] = __builtin_amdgcn_mfma_f32_16x16x32_bf16(Bt[n][k], At[m][k], acc[ai][bj][m][n], 0, 0, 0); __builtin_amdgcn_s_setprio(0); } while (0)
; #define G_WAIT_V(n) asm volatile("s_waitcnt vmcnt(" #n ")" ::: "memory")
; #define G_WAIT_L(n) asm volatile("s_waitcnt lgkmcnt(" #n ")" ::: "memory")
; #define G_BAR __builtin_amdgcn_s_barrier()
; #define G_SCHED __builtin_amdgcn_sched_barrier(0)
; template <int MODE>
; __device__ __forceinline__ void gemm_phase(const Params& p, int layer, char* lds_generic) {
;     ...
;       G_WAIT_V(6); G_BAR; G_MMA(1, 1, At, B1); G_BAR;
;       G_LDB(B0, 1, 0); G_SCHED; G_LDA(At, 1, 0); G_STAGE(G_SA(0, 1), a2 + hstep);
;       G_WAIT_L(8); G_BAR; G_WAIT_L(0); G_MMA(0, 0, At, B0); G_BAR; G_SCHED;
;       G_LDB(B1, 1, 1); G_STAGE(G_SB(1, 0), b3);
;       G_BAR; G_WAIT_L(0); G_MMA(0, 1, At, B1); G_BAR;
;       G_LDA(At, 1, 1); G_STAGE(G_SA(1, 0), a3);
;       G_BAR; G_WAIT_L(0); G_MMA(1, 0, At, B0); G_BAR; G_SCHED;
	v_mfma_f32_16x16x32_bf16 v[48:51], v[206:209], v[172:175], v[48:51]
	v_mfma_f32_16x16x32_bf16 v[40:43], v[222:225], v[172:175], v[40:43]
	v_mfma_f32_16x16x32_bf16 v[32:35], v[206:209], v[180:183], v[32:35]
	v_mfma_f32_16x16x32_bf16 v[24:27], v[222:225], v[180:183], v[24:27]
	v_mfma_f32_16x16x32_bf16 v[16:19], v[206:209], v[188:191], v[16:19]
	v_mfma_f32_16x16x32_bf16 v[8:11], v[222:225], v[188:191], v[8:11]
	v_mfma_f32_16x16x32_bf16 v[4:7], v[206:209], v[198:201], v[4:7]
	v_mfma_f32_16x16x32_bf16 v[0:3], v[222:225], v[198:201], v[0:3]
	v_mfma_f32_16x16x32_bf16 v[48:51], v[216:219], v[176:179], v[48:51]
	v_mfma_f32_16x16x32_bf16 v[40:43], v[228:231], v[176:179], v[40:43]
	v_mfma_f32_16x16x32_bf16 v[32:35], v[216:219], v[184:187], v[32:35]
	v_mfma_f32_16x16x32_bf16 v[24:27], v[228:231], v[184:187], v[24:27]
	v_mfma_f32_16x16x32_bf16 v[16:19], v[216:219], v[194:197], v[16:19]
	v_mfma_f32_16x16x32_bf16 v[8:11], v[228:231], v[194:197], v[8:11]
	v_mfma_f32_16x16x32_bf16 v[4:7], v[216:219], v[202:205], v[4:7]
	v_mfma_f32_16x16x32_bf16 v[0:3], v[228:231], v[202:205], v[0:3]
	s_barrier
	ds_read_b128 v[156:159], v147
	ds_read_b128 v[160:163], v148
	ds_read_b128 v[164:167], v149
	ds_read_b128 v[168:171], v150
	s_add_u32 s12, s86, 0x80000
	s_addc_u32 s13, s87, 0
	s_mov_b32 m0, s83
	v_lshl_add_u64 v[206:207], s[12:13], 0, v[192:193]
	ds_read_b128 v[172:175], v137 offset:32768
	ds_read_b128 v[176:179], v137 offset:33792
	ds_read_b128 v[180:183], v137 offset:34816
	ds_read_b128 v[184:187], v137 offset:35840
	ds_read_b128 v[188:191], v137 offset:36864
	ds_read_b128 v[194:197], v137 offset:37888
	ds_read_b128 v[198:201], v137 offset:38912
	ds_read_b128 v[202:205], v137 offset:39936
	global_load_lds_dwordx4 v[206:207], off
	v_lshl_add_u64 v[206:207], s[12:13], 0, v[128:129]
	s_mov_b32 m0, s84
	s_nop 0
	global_load_lds_dwordx4 v[206:207], off
	s_waitcnt lgkmcnt(8)
	s_barrier
	s_waitcnt lgkmcnt(0)
	v_mfma_f32_16x16x32_bf16 v[124:127], v[156:159], v[172:175], v[124:127]
	v_mfma_f32_16x16x32_bf16 v[120:123], v[164:167], v[172:175], v[120:123]
	v_mfma_f32_16x16x32_bf16 v[116:119], v[156:159], v[180:183], v[116:119]
	v_mfma_f32_16x16x32_bf16 v[108:111], v[164:167], v[180:183], v[108:111]
	v_mfma_f32_16x16x32_bf16 v[100:103], v[156:159], v[188:191], v[100:103]
	v_mfma_f32_16x16x32_bf16 v[92:95], v[164:167], v[188:191], v[92:95]
	v_mfma_f32_16x16x32_bf16 v[84:87], v[156:159], v[198:201], v[84:87]
	v_mfma_f32_16x16x32_bf16 v[76:79], v[164:167], v[198:201], v[76:79]
	v_mfma_f32_16x16x32_bf16 v[124:127], v[160:163], v[176:179], v[124:127]
	v_mfma_f32_16x16x32_bf16 v[120:123], v[168:171], v[176:179], v[120:123]
	v_mfma_f32_16x16x32_bf16 v[116:119], v[160:163], v[184:187], v[116:119]
	v_mfma_f32_16x16x32_bf16 v[108:111], v[168:171], v[184:187], v[108:111]
	v_mfma_f32_16x16x32_bf16 v[100:103], v[160:163], v[194:197], v[100:103]
	v_mfma_f32_16x16x32_bf16 v[92:95], v[168:171], v[194:197], v[92:95]
	v_mfma_f32_16x16x32_bf16 v[84:87], v[160:163], v[202:205], v[84:87]
	v_mfma_f32_16x16x32_bf16 v[76:79], v[168:171], v[202:205], v[76:79]
	s_barrier
	s_mov_b32 m0, s85
	v_lshl_add_u64 v[134:135], v[134:135], 0, s[90:91]
	ds_read_b128 v[206:209], v151
	ds_read_b128 v[216:219], v152
	ds_read_b128 v[222:225], v153
	ds_read_b128 v[228:231], v154
	global_load_lds_dwordx4 v[134:135], off
	v_lshl_add_u64 v[134:135], v[210:211], 0, s[90:91]
	s_mov_b32 m0, s88
	s_nop 0
	global_load_lds_dwordx4 v[134:135], off
	s_barrier
	s_waitcnt lgkmcnt(0)
	v_mfma_f32_16x16x32_bf16 v[112:115], v[206:209], v[172:175], v[112:115]
	v_mfma_f32_16x16x32_bf16 v[104:107], v[222:225], v[172:175], v[104:107]
	v_mfma_f32_16x16x32_bf16 v[96:99], v[206:209], v[180:183], v[96:99]
	v_mfma_f32_16x16x32_bf16 v[88:91], v[222:225], v[180:183], v[88:91]
	v_mfma_f32_16x16x32_bf16 v[80:83], v[206:209], v[188:191], v[80:83]
	v_mfma_f32_16x16x32_bf16 v[72:75], v[222:225], v[188:191], v[72:75]
	v_mfma_f32_16x16x32_bf16 v[68:71], v[206:209], v[198:201], v[68:71]
	v_mfma_f32_16x16x32_bf16 v[64:67], v[222:225], v[198:201], v[64:67]
	v_mfma_f32_16x16x32_bf16 v[112:115], v[216:219], v[176:179], v[112:115]
	v_mfma_f32_16x16x32_bf16 v[104:107], v[228:231], v[176:179], v[104:107]
	v_mfma_f32_16x16x32_bf16 v[96:99], v[216:219], v[184:187], v[96:99]
	v_mfma_f32_16x16x32_bf16 v[88:91], v[228:231], v[184:187], v[88:91]
	v_mfma_f32_16x16x32_bf16 v[80:83], v[216:219], v[194:197], v[80:83]
	v_mfma_f32_16x16x32_bf16 v[72:75], v[228:231], v[194:197], v[72:75]
	v_mfma_f32_16x16x32_bf16 v[68:71], v[216:219], v[202:205], v[68:71]
	v_mfma_f32_16x16x32_bf16 v[64:67], v[228:231], v[202:205], v[64:67]
	s_mov_b32 m0, s89
	v_lshl_add_u64 v[134:135], v[232:233], 0, s[90:91]
	s_barrier
	ds_read_b128 v[172:175], v137 offset:49152
	ds_read_b128 v[176:179], v137 offset:50176
	ds_read_b128 v[180:183], v137 offset:51200
	ds_read_b128 v[184:187], v137 offset:52224
	ds_read_b128 v[188:191], v137 offset:53248
	ds_read_b128 v[194:197], v137 offset:54272
	ds_read_b128 v[198:201], v137 offset:55296
	ds_read_b128 v[202:205], v137 offset:56320
	global_load_lds_dwordx4 v[134:135], off
	v_lshl_add_u64 v[134:135], v[234:235], 0, s[90:91]
	s_mov_b32 m0, s92
	s_nop 0
	global_load_lds_dwordx4 v[134:135], off
	s_barrier
; #define G_STAGE(bufoff, gbase) do { _Pragma("unroll") for (int _i = 0; _i < 2; ++_i) \
;     __builtin_amdgcn_global_load_lds((const unsigned*)((const char*)(gbase) + voffA[_i]), (LAS unsigned*)(lds + (bufoff) + ldsw + _i * 8192), 16, 0, 0); } while (0)
; #define G_MMA(ai, bj, At, Bt) do { __builtin_amdgcn_s_setprio(1); _Pragma("unroll") for (int m = 0; m < 4; ++m) _Pragma("unroll") for (int n = 0; n < 2; ++n) _Pragma("unroll") for (int k = 0; k < 2; ++k) \
;     acc[ai][bj][m][n] = __builtin_amdgcn_mfma_f32_16x16x32_bf16(Bt[n][k], At[m][k], acc[ai][bj][m][n], 0, 0, 0); __builtin_amdgcn_s_setprio(0); } while (0)
; #define G_WAIT_V(n) asm volatile("s_waitcnt vmcnt(" #n ")" ::: "memory")
; #define G_WAIT_L(n) asm volatile("s_waitcnt lgkmcnt(" #n ")" ::: "memory")
; #define G_BAR __builtin_amdgcn_s_barrier()
; #define G_SCHED __builtin_amdgcn_sched_barrier(0)
; template <int MODE>
; __device__ __forceinline__ void gemm_phase(const Params& p, int layer, char* lds_generic) {
;     ...
;       G_BAR; G_WAIT_L(0); G_MMA(1, 0, At, B0); G_BAR; G_SCHED;
;       G_STAGE(G_SB(1, 1), b3 + hstep);
;       G_WAIT_V(6); G_BAR; G_MMA(1, 1, At, B1); G_BAR;
;     }
	s_waitcnt lgkmcnt(0)
	v_mfma_f32_16x16x32_bf16 v[60:63], v[156:159], v[172:175], v[60:63]
	v_mfma_f32_16x16x32_bf16 v[56:59], v[164:167], v[172:175], v[56:59]
	v_mfma_f32_16x16x32_bf16 v[52:55], v[156:159], v[180:183], v[52:55]
	v_mfma_f32_16x16x32_bf16 v[44:47], v[164:167], v[180:183], v[44:47]
	v_mfma_f32_16x16x32_bf16 v[36:39], v[156:159], v[188:191], v[36:39]
	v_mfma_f32_16x16x32_bf16 v[28:31], v[164:167], v[188:191], v[28:31]
	v_mfma_f32_16x16x32_bf16 v[20:23], v[156:159], v[198:201], v[20:23]
	v_mfma_f32_16x16x32_bf16 v[12:15], v[164:167], v[198:201], v[12:15]
	v_mfma_f32_16x16x32_bf16 v[60:63], v[160:163], v[176:179], v[60:63]
	v_mfma_f32_16x16x32_bf16 v[56:59], v[168:171], v[176:179], v[56:59]
	v_mfma_f32_16x16x32_bf16 v[52:55], v[160:163], v[184:187], v[52:55]
	v_mfma_f32_16x16x32_bf16 v[44:47], v[168:171], v[184:187], v[44:47]
	v_mfma_f32_16x16x32_bf16 v[36:39], v[160:163], v[194:197], v[36:39]
	v_mfma_f32_16x16x32_bf16 v[28:31], v[168:171], v[194:197], v[28:31]
	v_mfma_f32_16x16x32_bf16 v[20:23], v[160:163], v[202:205], v[20:23]
	v_mfma_f32_16x16x32_bf16 v[12:15], v[168:171], v[202:205], v[12:15]
	s_barrier
	s_add_u32 s12, s74, 0x80080
	s_addc_u32 s13, s75, 0
	s_mov_b32 m0, s94
	v_lshl_add_u64 v[134:135], s[12:13], 0, v[192:193]
	global_load_lds_dwordx4 v[134:135], off
	v_lshl_add_u64 v[134:135], s[12:13], 0, v[128:129]
	s_mov_b32 m0, s95
	s_nop 0
	global_load_lds_dwordx4 v[134:135], off
	s_waitcnt vmcnt(6)
	s_barrier
	v_mfma_f32_16x16x32_bf16 v[48:51], v[206:209], v[172:175], v[48:51]
	v_mfma_f32_16x16x32_bf16 v[40:43], v[222:225], v[172:175], v[40:43]
	v_mfma_f32_16x16x32_bf16 v[32:35], v[206:209], v[180:183], v[32:35]
	v_mfma_f32_16x16x32_bf16 v[24:27], v[222:225], v[180:183], v[24:27]
	v_mfma_f32_16x16x32_bf16 v[16:19], v[206:209], v[188:191], v[16:19]
	v_mfma_f32_16x16x32_bf16 v[8:11], v[222:225], v[188:191], v[8:11]
	v_mfma_f32_16x16x32_bf16 v[4:7], v[206:209], v[198:201], v[4:7]
	v_mfma_f32_16x16x32_bf16 v[0:3], v[222:225], v[198:201], v[0:3]
	v_mfma_f32_16x16x32_bf16 v[48:51], v[216:219], v[176:179], v[48:51]
	v_mfma_f32_16x16x32_bf16 v[40:43], v[228:231], v[176:179], v[40:43]
	v_mfma_f32_16x16x32_bf16 v[32:35], v[216:219], v[184:187], v[32:35]
	v_mfma_f32_16x16x32_bf16 v[24:27], v[228:231], v[184:187], v[24:27]
	v_mfma_f32_16x16x32_bf16 v[16:19], v[216:219], v[194:197], v[16:19]
	v_mfma_f32_16x16x32_bf16 v[8:11], v[228:231], v[194:197], v[8:11]
	v_mfma_f32_16x16x32_bf16 v[4:7], v[216:219], v[202:205], v[4:7]
	v_mfma_f32_16x16x32_bf16 v[0:3], v[228:231], v[202:205], v[0:3]
	s_add_i32 s9, s9, 2
	s_add_u32 s78, s78, 0x100
	s_addc_u32 s79, s79, 0
	s_add_u32 s5, s5, 0x100
	s_addc_u32 s8, s8, 0
	s_cmp_gt_u32 s9, 29
	s_barrier
	s_cbranch_scc0 .LBB0_88
;   __device__ __forceinline__ float* S() const { return (float*)(ws + 456 * MB); }
; #define G_WAIT_V(n) asm volatile("s_waitcnt vmcnt(" #n ")" ::: "memory")
; #define G_BAR __builtin_amdgcn_s_barrier()
; template <int MODE>
; __device__ __forceinline__ void gemm_epilogue(const Params& p, int layer, const f32x4 (&acc)[2][2][4][2], int pm, int pn, int wr, int wc, int fr, int fq) {
;     ...
;       } else {
; #pragma unroll
;         for (int bj = 0; bj < 2; ++bj) { const int col = pn * 256 + bj * 128 + wc * 32 + 8 * fq; const f32x4 a0 = acc[ai][bj][m][0], a1 = acc[ai][bj][m][1];
;           const u32x4 w = {cvtpk(a0[0], a0[1]), cvtpk(a0[2], a0[3]), cvtpk(a1[0], a1[1]), cvtpk(a1[2], a1[3])};
;           *(u32x4*)((bf16_t*)p.S() + (size_t)row * DM + col) = w; }
;       }
; template <int MODE>
; __device__ __forceinline__ void gemm_phase(const Params& p, int layer, char* lds_generic) {
;     ...
;     gemm_epilogue<MODE>(p, layer, acc, cpm, cpn, wr, wc, fr, fq);
;     if (!has_next) break;
; #pragma unroll
;     for (int a = 0; a < 2; ++a)
; #pragma unroll
;       for (int b = 0; b < 2; ++b)
; #pragma unroll
;         for (int m = 0; m < 4; ++m)
; #pragma unroll
;           for (int n = 0; n < 2; ++n) acc[a][b][m][n] = (f32x4){0.f, 0.f, 0.f, 0.f};
;     cpm = npm; cpn = npn; cA = nA; cB = nB; ++ui;
;   }
;   G_WAIT_V(0);
;   if (wr == 0) G_BAR;
;   G_BAR;
	v_lshl_add_u32 v134, s4, 8, v136
	v_lshl_or_b32 v156, s2, 8, v138
	v_ashrrev_i32_e32 v135, 31, v134
	v_lshlrev_b64 v[158:159], 12, v[134:135]
	v_ashrrev_i32_e32 v157, 31, v156
	v_cvt_pk_bf16_f32 v124, v124, v125
	v_cvt_pk_bf16_f32 v125, v126, v127
	v_cvt_pk_bf16_f32 v126, v120, v121
	v_cvt_pk_bf16_f32 v127, v122, v123
	v_lshl_add_u64 v[122:123], s[6:7], 0, v[158:159]
	v_lshlrev_b64 v[120:121], 1, v[156:157]
	v_lshl_add_u64 v[122:123], v[122:123], 0, v[120:121]
	global_store_dwordx4 v[122:123], v[124:127], off
	v_cvt_pk_bf16_f32 v112, v112, v113
	v_cvt_pk_bf16_f32 v113, v114, v115
	v_cvt_pk_bf16_f32 v114, v104, v105
	v_or_b32_e32 v104, 16, v134
	v_ashrrev_i32_e32 v105, 31, v104
	v_cvt_pk_bf16_f32 v115, v106, v107
	global_store_dwordx4 v[122:123], v[112:115], off offset:256
	s_and_b64 vcc, exec, s[70:71]
	s_mov_b32 s4, s66
	v_lshlrev_b64 v[112:113], 12, v[104:105]
	v_cvt_pk_bf16_f32 v104, v116, v117
	v_cvt_pk_bf16_f32 v105, v118, v119
	v_cvt_pk_bf16_f32 v106, v108, v109
	v_lshl_add_u64 v[108:109], s[6:7], 0, v[112:113]
	v_lshl_add_u64 v[108:109], v[108:109], 0, v[120:121]
	v_cvt_pk_bf16_f32 v107, v110, v111
	global_store_dwordx4 v[108:109], v[104:107], off
	v_cvt_pk_bf16_f32 v96, v96, v97
	v_cvt_pk_bf16_f32 v97, v98, v99
	v_cvt_pk_bf16_f32 v98, v88, v89
	v_or_b32_e32 v88, 32, v134
	v_ashrrev_i32_e32 v89, 31, v88
	v_cvt_pk_bf16_f32 v99, v90, v91
	global_store_dwordx4 v[108:109], v[96:99], off offset:256
	s_mov_b32 s2, s68
	s_mov_b64 s[74:75], s[76:77]
	v_lshlrev_b64 v[96:97], 12, v[88:89]
	v_cvt_pk_bf16_f32 v88, v100, v101
	v_cvt_pk_bf16_f32 v89, v102, v103
	v_cvt_pk_bf16_f32 v90, v92, v93
	v_lshl_add_u64 v[92:93], s[6:7], 0, v[96:97]
	v_lshl_add_u64 v[92:93], v[92:93], 0, v[120:121]
	v_cvt_pk_bf16_f32 v91, v94, v95
	global_store_dwordx4 v[92:93], v[88:91], off
	v_cvt_pk_bf16_f32 v80, v80, v81
	v_cvt_pk_bf16_f32 v81, v82, v83
	v_cvt_pk_bf16_f32 v82, v72, v73
	v_or_b32_e32 v72, 48, v134
	v_ashrrev_i32_e32 v73, 31, v72
	v_cvt_pk_bf16_f32 v83, v74, v75
	global_store_dwordx4 v[92:93], v[80:83], off offset:256
	s_mov_b64 s[78:79], s[72:73]
	s_nop 0
	v_lshlrev_b64 v[80:81], 12, v[72:73]
	v_cvt_pk_bf16_f32 v72, v84, v85
	v_cvt_pk_bf16_f32 v73, v86, v87
	v_cvt_pk_bf16_f32 v74, v76, v77
	v_lshl_add_u64 v[76:77], s[6:7], 0, v[80:81]
	v_lshl_add_u64 v[76:77], v[76:77], 0, v[120:121]
	v_cvt_pk_bf16_f32 v75, v78, v79
	global_store_dwordx4 v[76:77], v[72:75], off
	v_cvt_pk_bf16_f32 v68, v68, v69
	v_cvt_pk_bf16_f32 v69, v70, v71
	v_cvt_pk_bf16_f32 v70, v64, v65
	v_add_u32_e32 v64, 0x80, v134
	v_ashrrev_i32_e32 v65, 31, v64
	v_lshlrev_b64 v[64:65], 12, v[64:65]
	v_cvt_pk_bf16_f32 v71, v66, v67
	global_store_dwordx4 v[76:77], v[68:71], off offset:256
	v_cvt_pk_bf16_f32 v60, v60, v61
	v_cvt_pk_bf16_f32 v61, v62, v63
	v_cvt_pk_bf16_f32 v62, v56, v57
	v_lshl_add_u64 v[56:57], s[6:7], 0, v[64:65]
	v_lshl_add_u64 v[56:57], v[56:57], 0, v[120:121]
	v_cvt_pk_bf16_f32 v63, v58, v59
	global_store_dwordx4 v[56:57], v[60:63], off
	v_cvt_pk_bf16_f32 v48, v48, v49
	v_cvt_pk_bf16_f32 v49, v50, v51
	v_cvt_pk_bf16_f32 v50, v40, v41
	v_add_u32_e32 v40, 0x90, v134
	v_ashrrev_i32_e32 v41, 31, v40
	v_cvt_pk_bf16_f32 v51, v42, v43
	global_store_dwordx4 v[56:57], v[48:51], off offset:256
	s_nop 1
	v_lshlrev_b64 v[48:49], 12, v[40:41]
	v_cvt_pk_bf16_f32 v40, v52, v53
	v_cvt_pk_bf16_f32 v41, v54, v55
	v_cvt_pk_bf16_f32 v42, v44, v45
	v_lshl_add_u64 v[44:45], s[6:7], 0, v[48:49]
	v_lshl_add_u64 v[44:45], v[44:45], 0, v[120:121]
	v_cvt_pk_bf16_f32 v43, v46, v47
	global_store_dwordx4 v[44:45], v[40:43], off
	v_cvt_pk_bf16_f32 v32, v32, v33
	v_cvt_pk_bf16_f32 v33, v34, v35
	v_cvt_pk_bf16_f32 v34, v24, v25
	v_add_u32_e32 v24, 0xa0, v134
	v_ashrrev_i32_e32 v25, 31, v24
	v_cvt_pk_bf16_f32 v35, v26, v27
	global_store_dwordx4 v[44:45], v[32:35], off offset:256
	s_nop 1
	v_lshlrev_b64 v[32:33], 12, v[24:25]
	v_cvt_pk_bf16_f32 v24, v36, v37
	v_cvt_pk_bf16_f32 v25, v38, v39
	v_cvt_pk_bf16_f32 v26, v28, v29
	v_lshl_add_u64 v[28:29], s[6:7], 0, v[32:33]
	v_lshl_add_u64 v[28:29], v[28:29], 0, v[120:121]
	v_cvt_pk_bf16_f32 v27, v30, v31
	global_store_dwordx4 v[28:29], v[24:27], off
	v_cvt_pk_bf16_f32 v16, v16, v17
	v_cvt_pk_bf16_f32 v17, v18, v19
	v_cvt_pk_bf16_f32 v18, v8, v9
	v_add_u32_e32 v8, 0xb0, v134
	v_ashrrev_i32_e32 v9, 31, v8
	v_cvt_pk_bf16_f32 v19, v10, v11
	global_store_dwordx4 v[28:29], v[16:19], off offset:256
	s_nop 1
	v_lshlrev_b64 v[16:17], 12, v[8:9]
	v_cvt_pk_bf16_f32 v8, v20, v21
	v_cvt_pk_bf16_f32 v9, v22, v23
	v_cvt_pk_bf16_f32 v10, v12, v13
	v_lshl_add_u64 v[12:13], s[6:7], 0, v[16:17]
	v_lshl_add_u64 v[12:13], v[12:13], 0, v[120:121]
	v_cvt_pk_bf16_f32 v11, v14, v15
	global_store_dwordx4 v[12:13], v[8:11], off
	v_cvt_pk_bf16_f32 v4, v4, v5
	v_cvt_pk_bf16_f32 v5, v6, v7
	v_cvt_pk_bf16_f32 v6, v0, v1
	v_cvt_pk_bf16_f32 v7, v2, v3
	global_store_dwordx4 v[12:13], v[4:7], off offset:256
	s_cbranch_vccz .LBB0_85
	s_waitcnt vmcnt(0)
	s_cmpk_gt_u32 s16, 0xff
	v_readlane_b32 s92, v254, 32
	s_mov_b32 s88, 0x8000
	s_movk_i32 s89, 0x1400
	s_movk_i32 s66, 0x78
	s_cbranch_scc1 .LBB0_92
	s_barrier

; #define G_STAGE(bufoff, gbase) do { _Pragma("unroll") for (int _i = 0; _i < 2; ++_i) \
;     __builtin_amdgcn_global_load_lds((const unsigned*)((const char*)(gbase) + voffA[_i]), (LAS unsigned*)(lds + (bufoff) + ldsw + _i * 8192), 16, 0, 0); } while (0)
; #define G_LDA(dst, b, h) do { _Pragma("unroll") for (int m = 0; m < 4; ++m) _Pragma("unroll") for (int k = 0; k < 2; ++k) dst[m][k] = *(const LAS bf16x8*)(lds + G_SA(b, h) + aoff + m * 2048 + k * 1024); } while (0)
; #define G_LDB(dst, b, h) do { _Pragma("unroll") for (int n = 0; n < 2; ++n) _Pragma("unroll") for (int k = 0; k < 2; ++k) dst[n][k] = *(const LAS bf16x8*)(lds + G_SB(b, h) + boff + n * 2048 + k * 1024); } while (0)
; #define G_MMA(ai, bj, At, Bt) do { __builtin_amdgcn_s_setprio(1); _Pragma("unroll") for (int m = 0; m < 4; ++m) _Pragma("unroll") for (int n = 0; n < 2; ++n) _Pragma("unroll") for (int k = 0; k < 2; ++k) \
;     acc[ai][bj][m][n] = __builtin_amdgcn_mfma_f32_16x16x32_bf16(Bt[n][k], At[m][k], acc[ai][bj][m][n], 0, 0, 0); __builtin_amdgcn_s_setprio(0); } while (0)
; #define G_WAIT_L(n) asm volatile("s_waitcnt lgkmcnt(" #n ")" ::: "memory")
; #define G_BAR __builtin_amdgcn_s_barrier()
; #define G_SCHED __builtin_amdgcn_sched_barrier(0)
; template <int MODE>
; __device__ __forceinline__ void gemm_phase(const Params& p, int layer, char* lds_generic) {
;     ...
;       G_LDB(B0, 0, 0); G_SCHED; G_LDA(At, 0, 0); G_STAGE(G_SA(1, 1), a1 + hstep);
;       G_WAIT_L(8); G_BAR; G_WAIT_L(0); G_MMA(0, 0, At, B0); G_BAR; G_SCHED;
;       G_LDB(B1, 0, 1); G_STAGE(G_SB(0, 0), b2);
;       G_BAR; G_WAIT_L(0); G_MMA(0, 1, At, B1); G_BAR;
;       G_LDA(At, 0, 1); G_STAGE(G_SA(0, 0), a2);
;       G_BAR; G_WAIT_L(0); G_MMA(1, 0, At, B0); G_BAR; G_SCHED;
.LBB0_103:
	v_or_b32_e32 v134, 0x10000, v140
	v_add_u32_e32 v142, 0x10400, v140
	v_add_u32_e32 v146, 0x10800, v140
	v_add_u32_e32 v150, 0x10c00, v140
	ds_read_b128 v[134:137], v134
	ds_read_b128 v[142:145], v142
	ds_read_b128 v[146:149], v146
	ds_read_b128 v[150:153], v150
	s_add_u32 s12, vcc_lo, 0xfff80080
	s_addc_u32 s13, vcc_hi, -1
	s_cmp_eq_u32 s9, 28
	s_cselect_b32 s79, s2, s13
	s_cselect_b32 s78, s69, s12
	s_cselect_b32 s77, s71, s60
	s_cselect_b32 s76, s88, s89
	v_lshl_add_u64 v[186:187], vcc, 0, v[130:131]
	s_add_i32 m0, s8, 0xc000
	ds_read_b128 v[154:157], v139
	ds_read_b128 v[158:161], v139 offset:1024
	ds_read_b128 v[162:165], v139 offset:2048
	ds_read_b128 v[166:169], v139 offset:3072
	ds_read_b128 v[170:173], v139 offset:4096
	ds_read_b128 v[174:177], v139 offset:5120
	ds_read_b128 v[178:181], v139 offset:6144
	ds_read_b128 v[182:185], v139 offset:7168
	global_load_lds_dwordx4 v[186:187], off
	v_lshl_add_u64 v[186:187], vcc, 0, v[132:133]
	s_add_i32 m0, s8, 0xe000
	s_nop 0
	global_load_lds_dwordx4 v[186:187], off
	s_waitcnt lgkmcnt(8)
	s_barrier
	s_waitcnt lgkmcnt(0)
	v_mfma_f32_16x16x32_bf16 v[124:127], v[134:137], v[154:157], v[124:127]
	v_mfma_f32_16x16x32_bf16 v[120:123], v[146:149], v[154:157], v[120:123]
	v_mfma_f32_16x16x32_bf16 v[108:111], v[134:137], v[162:165], v[108:111]
	v_mfma_f32_16x16x32_bf16 v[104:107], v[146:149], v[162:165], v[104:107]
	v_mfma_f32_16x16x32_bf16 v[92:95], v[134:137], v[170:173], v[92:95]
	v_mfma_f32_16x16x32_bf16 v[88:91], v[146:149], v[170:173], v[88:91]
	v_mfma_f32_16x16x32_bf16 v[76:79], v[134:137], v[178:181], v[76:79]
	v_mfma_f32_16x16x32_bf16 v[72:75], v[146:149], v[178:181], v[72:75]
	v_mfma_f32_16x16x32_bf16 v[124:127], v[142:145], v[158:161], v[124:127]
	v_mfma_f32_16x16x32_bf16 v[120:123], v[150:153], v[158:161], v[120:123]
	v_mfma_f32_16x16x32_bf16 v[108:111], v[142:145], v[166:169], v[108:111]
	v_mfma_f32_16x16x32_bf16 v[104:107], v[150:153], v[166:169], v[104:107]
	v_mfma_f32_16x16x32_bf16 v[92:95], v[142:145], v[174:177], v[92:95]
	v_mfma_f32_16x16x32_bf16 v[88:91], v[150:153], v[174:177], v[88:91]
	v_mfma_f32_16x16x32_bf16 v[76:79], v[142:145], v[182:185], v[76:79]
	v_mfma_f32_16x16x32_bf16 v[72:75], v[150:153], v[182:185], v[72:75]
	s_barrier
	v_or_b32_e32 v186, 0x14000, v140
	v_add_u32_e32 v190, 0x14400, v140
	ds_read_b128 v[186:189], v186
	ds_read_b128 v[194:197], v190
	v_add_u32_e32 v190, 0x14800, v140
	v_add_u32_e32 v191, 0x14c00, v140
	s_mov_b32 m0, s92
	ds_read_b128 v[198:201], v190
	ds_read_b128 v[202:205], v191
	v_lshl_add_u64 v[190:191], s[76:77], 0, v[192:193]
	global_load_lds_dwordx4 v[190:191], off
	v_lshl_add_u64 v[206:207], s[76:77], 0, v[128:129]
	s_mov_b32 m0, s94
	s_nop 0
	global_load_lds_dwordx4 v[206:207], off
	s_barrier
	s_waitcnt lgkmcnt(0)
	v_mfma_f32_16x16x32_bf16 v[116:119], v[186:189], v[154:157], v[116:119]
	v_mfma_f32_16x16x32_bf16 v[112:115], v[198:201], v[154:157], v[112:115]
	v_mfma_f32_16x16x32_bf16 v[100:103], v[186:189], v[162:165], v[100:103]
	v_mfma_f32_16x16x32_bf16 v[96:99], v[198:201], v[162:165], v[96:99]
	v_mfma_f32_16x16x32_bf16 v[84:87], v[186:189], v[170:173], v[84:87]
	v_mfma_f32_16x16x32_bf16 v[80:83], v[198:201], v[170:173], v[80:83]
	v_mfma_f32_16x16x32_bf16 v[68:71], v[186:189], v[178:181], v[68:71]
	v_mfma_f32_16x16x32_bf16 v[64:67], v[198:201], v[178:181], v[64:67]
	v_mfma_f32_16x16x32_bf16 v[116:119], v[194:197], v[158:161], v[116:119]
	v_mfma_f32_16x16x32_bf16 v[112:115], v[202:205], v[158:161], v[112:115]
	v_mfma_f32_16x16x32_bf16 v[100:103], v[194:197], v[166:169], v[100:103]
	v_mfma_f32_16x16x32_bf16 v[96:99], v[202:205], v[166:169], v[96:99]
	v_mfma_f32_16x16x32_bf16 v[84:87], v[194:197], v[174:177], v[84:87]
	v_mfma_f32_16x16x32_bf16 v[80:83], v[202:205], v[174:177], v[80:83]
	v_mfma_f32_16x16x32_bf16 v[68:71], v[194:197], v[182:185], v[68:71]
	v_mfma_f32_16x16x32_bf16 v[64:67], v[202:205], v[182:185], v[64:67]
	s_mov_b32 m0, s8
	v_lshl_add_u64 v[208:209], s[78:79], 0, v[192:193]
	s_barrier
	ds_read_b128 v[154:157], v139 offset:16384
	ds_read_b128 v[158:161], v139 offset:17408
	ds_read_b128 v[162:165], v139 offset:18432
	ds_read_b128 v[166:169], v139 offset:19456
	ds_read_b128 v[170:173], v139 offset:20480
	ds_read_b128 v[174:177], v139 offset:21504
	ds_read_b128 v[178:181], v139 offset:22528
	ds_read_b128 v[182:185], v139 offset:23552
	global_load_lds_dwordx4 v[208:209], off
	v_lshl_add_u64 v[210:211], s[78:79], 0, v[128:129]
	s_mov_b32 m0, s33
	s_nop 0
	global_load_lds_dwordx4 v[210:211], off
	s_barrier
	s_waitcnt lgkmcnt(0)
	v_mfma_f32_16x16x32_bf16 v[60:63], v[134:137], v[154:157], v[60:63]
	v_mfma_f32_16x16x32_bf16 v[56:59], v[146:149], v[154:157], v[56:59]
	v_mfma_f32_16x16x32_bf16 v[44:47], v[134:137], v[162:165], v[44:47]
	v_mfma_f32_16x16x32_bf16 v[40:43], v[146:149], v[162:165], v[40:43]
	v_mfma_f32_16x16x32_bf16 v[28:31], v[134:137], v[170:173], v[28:31]
	v_mfma_f32_16x16x32_bf16 v[24:27], v[146:149], v[170:173], v[24:27]
	v_mfma_f32_16x16x32_bf16 v[12:15], v[134:137], v[178:181], v[12:15]
	v_mfma_f32_16x16x32_bf16 v[8:11], v[146:149], v[178:181], v[8:11]
	v_mfma_f32_16x16x32_bf16 v[60:63], v[142:145], v[158:161], v[60:63]
	v_mfma_f32_16x16x32_bf16 v[56:59], v[150:153], v[158:161], v[56:59]
	v_mfma_f32_16x16x32_bf16 v[44:47], v[142:145], v[166:169], v[44:47]
	v_mfma_f32_16x16x32_bf16 v[40:43], v[150:153], v[166:169], v[40:43]
	v_mfma_f32_16x16x32_bf16 v[28:31], v[142:145], v[174:177], v[28:31]
	v_mfma_f32_16x16x32_bf16 v[24:27], v[150:153], v[174:177], v[24:27]
	v_mfma_f32_16x16x32_bf16 v[12:15], v[142:145], v[182:185], v[12:15]
	v_mfma_f32_16x16x32_bf16 v[8:11], v[150:153], v[182:185], v[8:11]
	s_barrier
; #define G_STAGE(bufoff, gbase) do { _Pragma("unroll") for (int _i = 0; _i < 2; ++_i) \
;     __builtin_amdgcn_global_load_lds((const unsigned*)((const char*)(gbase) + voffA[_i]), (LAS unsigned*)(lds + (bufoff) + ldsw + _i * 8192), 16, 0, 0); } while (0)
; #define G_LDA(dst, b, h) do { _Pragma("unroll") for (int m = 0; m < 4; ++m) _Pragma("unroll") for (int k = 0; k < 2; ++k) dst[m][k] = *(const LAS bf16x8*)(lds + G_SA(b, h) + aoff + m * 2048 + k * 1024); } while (0)
; #define G_LDB(dst, b, h) do { _Pragma("unroll") for (int n = 0; n < 2; ++n) _Pragma("unroll") for (int k = 0; k < 2; ++k) dst[n][k] = *(const LAS bf16x8*)(lds + G_SB(b, h) + boff + n * 2048 + k * 1024); } while (0)
; #define G_MMA(ai, bj, At, Bt) do { __builtin_amdgcn_s_setprio(1); _Pragma("unroll") for (int m = 0; m < 4; ++m) _Pragma("unroll") for (int n = 0; n < 2; ++n) _Pragma("unroll") for (int k = 0; k < 2; ++k) \
;     acc[ai][bj][m][n] = __builtin_amdgcn_mfma_f32_16x16x32_bf16(Bt[n][k], At[m][k], acc[ai][bj][m][n], 0, 0, 0); __builtin_amdgcn_s_setprio(0); } while (0)
; #define G_WAIT_V(n) asm volatile("s_waitcnt vmcnt(" #n ")" ::: "memory")
; #define G_WAIT_L(n) asm volatile("s_waitcnt lgkmcnt(" #n ")" ::: "memory")
; #define G_BAR __builtin_amdgcn_s_barrier()
; #define G_SCHED __builtin_amdgcn_sched_barrier(0)
; template <int MODE>
; __device__ __forceinline__ void gemm_phase(const Params& p, int layer, char* lds_generic) {
;     ...
;       G_STAGE(G_SB(0, 1), b2 + hstep);
;       G_WAIT_V(6); G_BAR; G_MMA(1, 1, At, B1); G_BAR;
;       G_LDB(B0, 1, 0); G_SCHED; G_LDA(At, 1, 0); G_STAGE(G_SA(0, 1), a2 + hstep);
;       G_WAIT_L(8); G_BAR; G_WAIT_L(0); G_MMA(0, 0, At, B0); G_BAR; G_SCHED;
;       G_LDB(B1, 1, 1); G_STAGE(G_SB(1, 0), b3);
;       G_BAR; G_WAIT_L(0); G_MMA(0, 1, At, B1); G_BAR;
;       G_LDA(At, 1, 1); G_STAGE(G_SA(1, 0), a3);
;       G_BAR; G_WAIT_L(0); G_MMA(1, 0, At, B0); G_BAR; G_SCHED;
	s_add_u32 s66, s76, 0x80000
	s_addc_u32 s67, s77, 0
	s_mov_b32 m0, s1
	v_lshl_add_u64 v[134:135], s[66:67], 0, v[192:193]
	global_load_lds_dwordx4 v[134:135], off
	v_lshl_add_u64 v[134:135], s[66:67], 0, v[128:129]
	s_mov_b32 m0, s34
	s_nop 0
	global_load_lds_dwordx4 v[134:135], off
	s_waitcnt vmcnt(6)
	s_barrier
	v_mfma_f32_16x16x32_bf16 v[52:55], v[186:189], v[154:157], v[52:55]
	v_mfma_f32_16x16x32_bf16 v[48:51], v[198:201], v[154:157], v[48:51]
	v_mfma_f32_16x16x32_bf16 v[36:39], v[186:189], v[162:165], v[36:39]
	v_mfma_f32_16x16x32_bf16 v[32:35], v[198:201], v[162:165], v[32:35]
	v_mfma_f32_16x16x32_bf16 v[20:23], v[186:189], v[170:173], v[20:23]
	v_mfma_f32_16x16x32_bf16 v[16:19], v[198:201], v[170:173], v[16:19]
	v_mfma_f32_16x16x32_bf16 v[4:7], v[186:189], v[178:181], v[4:7]
	v_mfma_f32_16x16x32_bf16 v[0:3], v[198:201], v[178:181], v[0:3]
	v_mfma_f32_16x16x32_bf16 v[52:55], v[194:197], v[158:161], v[52:55]
	v_mfma_f32_16x16x32_bf16 v[48:51], v[202:205], v[158:161], v[48:51]
	v_mfma_f32_16x16x32_bf16 v[36:39], v[194:197], v[166:169], v[36:39]
	v_mfma_f32_16x16x32_bf16 v[32:35], v[202:205], v[166:169], v[32:35]
	v_mfma_f32_16x16x32_bf16 v[20:23], v[194:197], v[174:177], v[20:23]
	v_mfma_f32_16x16x32_bf16 v[16:19], v[202:205], v[174:177], v[16:19]
	v_mfma_f32_16x16x32_bf16 v[4:7], v[194:197], v[182:185], v[4:7]
	v_mfma_f32_16x16x32_bf16 v[0:3], v[202:205], v[182:185], v[0:3]
	v_or_b32_e32 v134, 0x18000, v140
	v_add_u32_e32 v142, 0x18400, v140
	v_add_u32_e32 v146, 0x18800, v140
	v_add_u32_e32 v150, 0x18c00, v140
	s_barrier
	ds_read_b128 v[134:137], v134
	ds_read_b128 v[142:145], v142
	ds_read_b128 v[146:149], v146
	ds_read_b128 v[150:153], v150
	s_add_u32 s66, s78, 0x80000
	s_addc_u32 s67, s79, 0
	s_mov_b32 m0, s35
	v_lshl_add_u64 v[186:187], s[66:67], 0, v[192:193]
	ds_read_b128 v[154:157], v139 offset:32768
	ds_read_b128 v[158:161], v139 offset:33792
	ds_read_b128 v[162:165], v139 offset:34816
	ds_read_b128 v[166:169], v139 offset:35840
	ds_read_b128 v[170:173], v139 offset:36864
	ds_read_b128 v[174:177], v139 offset:37888
	ds_read_b128 v[178:181], v139 offset:38912
	ds_read_b128 v[182:185], v139 offset:39936
	global_load_lds_dwordx4 v[186:187], off
	v_lshl_add_u64 v[186:187], s[66:67], 0, v[128:129]
	s_mov_b32 m0, s4
	s_nop 0
	global_load_lds_dwordx4 v[186:187], off
	s_waitcnt lgkmcnt(8)
	s_barrier
	s_waitcnt lgkmcnt(0)
	v_mfma_f32_16x16x32_bf16 v[124:127], v[134:137], v[154:157], v[124:127]
	v_mfma_f32_16x16x32_bf16 v[120:123], v[146:149], v[154:157], v[120:123]
	v_mfma_f32_16x16x32_bf16 v[108:111], v[134:137], v[162:165], v[108:111]
	v_mfma_f32_16x16x32_bf16 v[104:107], v[146:149], v[162:165], v[104:107]
	v_mfma_f32_16x16x32_bf16 v[92:95], v[134:137], v[170:173], v[92:95]
	v_mfma_f32_16x16x32_bf16 v[88:91], v[146:149], v[170:173], v[88:91]
	v_mfma_f32_16x16x32_bf16 v[76:79], v[134:137], v[178:181], v[76:79]
	v_mfma_f32_16x16x32_bf16 v[72:75], v[146:149], v[178:181], v[72:75]
	v_mfma_f32_16x16x32_bf16 v[124:127], v[142:145], v[158:161], v[124:127]
	v_mfma_f32_16x16x32_bf16 v[120:123], v[150:153], v[158:161], v[120:123]
	v_mfma_f32_16x16x32_bf16 v[108:111], v[142:145], v[166:169], v[108:111]
	v_mfma_f32_16x16x32_bf16 v[104:107], v[150:153], v[166:169], v[104:107]
	v_mfma_f32_16x16x32_bf16 v[92:95], v[142:145], v[174:177], v[92:95]
	v_mfma_f32_16x16x32_bf16 v[88:91], v[150:153], v[174:177], v[88:91]
	v_mfma_f32_16x16x32_bf16 v[76:79], v[142:145], v[182:185], v[76:79]
	v_mfma_f32_16x16x32_bf16 v[72:75], v[150:153], v[182:185], v[72:75]
	s_barrier
	s_mov_b32 m0, s5
	v_or_b32_e32 v186, 0x1c000, v140
	v_add_u32_e32 v194, 0x1c400, v140
	v_add_u32_e32 v198, 0x1c800, v140
	v_add_u32_e32 v202, 0x1cc00, v140
	v_lshl_add_u64 v[190:191], v[190:191], 0, s[90:91]
	ds_read_b128 v[186:189], v186
	ds_read_b128 v[194:197], v194
	ds_read_b128 v[198:201], v198
	ds_read_b128 v[202:205], v202
	global_load_lds_dwordx4 v[190:191], off
	v_lshl_add_u64 v[190:191], v[206:207], 0, s[90:91]
	s_mov_b32 m0, s82
	s_nop 0
	global_load_lds_dwordx4 v[190:191], off
	s_barrier
	s_waitcnt lgkmcnt(0)
	v_mfma_f32_16x16x32_bf16 v[116:119], v[186:189], v[154:157], v[116:119]
	v_mfma_f32_16x16x32_bf16 v[112:115], v[198:201], v[154:157], v[112:115]
	v_mfma_f32_16x16x32_bf16 v[100:103], v[186:189], v[162:165], v[100:103]
	v_mfma_f32_16x16x32_bf16 v[96:99], v[198:201], v[162:165], v[96:99]
	v_mfma_f32_16x16x32_bf16 v[84:87], v[186:189], v[170:173], v[84:87]
	v_mfma_f32_16x16x32_bf16 v[80:83], v[198:201], v[170:173], v[80:83]
	v_mfma_f32_16x16x32_bf16 v[68:71], v[186:189], v[178:181], v[68:71]
	v_mfma_f32_16x16x32_bf16 v[64:67], v[198:201], v[178:181], v[64:67]
	v_mfma_f32_16x16x32_bf16 v[116:119], v[194:197], v[158:161], v[116:119]
	v_mfma_f32_16x16x32_bf16 v[112:115], v[202:205], v[158:161], v[112:115]
	v_mfma_f32_16x16x32_bf16 v[100:103], v[194:197], v[166:169], v[100:103]
	v_mfma_f32_16x16x32_bf16 v[96:99], v[202:205], v[166:169], v[96:99]
	v_mfma_f32_16x16x32_bf16 v[84:87], v[194:197], v[174:177], v[84:87]
	v_mfma_f32_16x16x32_bf16 v[80:83], v[202:205], v[174:177], v[80:83]
	v_mfma_f32_16x16x32_bf16 v[68:71], v[194:197], v[182:185], v[68:71]
	v_mfma_f32_16x16x32_bf16 v[64:67], v[202:205], v[182:185], v[64:67]
	s_mov_b32 m0, s83
	v_lshl_add_u64 v[190:191], v[208:209], 0, s[90:91]
	s_barrier
	ds_read_b128 v[154:157], v139 offset:49152
	ds_read_b128 v[158:161], v139 offset:50176
	ds_read_b128 v[162:165], v139 offset:51200
	ds_read_b128 v[166:169], v139 offset:52224
	ds_read_b128 v[170:173], v139 offset:53248
	ds_read_b128 v[174:177], v139 offset:54272
	ds_read_b128 v[178:181], v139 offset:55296
	ds_read_b128 v[182:185], v139 offset:56320
	global_load_lds_dwordx4 v[190:191], off
	v_lshl_add_u64 v[190:191], v[210:211], 0, s[90:91]
	s_mov_b32 m0, s84
	s_nop 0
	global_load_lds_dwordx4 v[190:191], off
	s_barrier
;   __device__ __forceinline__ bf16_t* XB() const { return (bf16_t*)(ws + 328 * MB); }
; #define G_STAGE(bufoff, gbase) do { _Pragma("unroll") for (int _i = 0; _i < 2; ++_i) \
;     __builtin_amdgcn_global_load_lds((const unsigned*)((const char*)(gbase) + voffA[_i]), (LAS unsigned*)(lds + (bufoff) + ldsw + _i * 8192), 16, 0, 0); } while (0)
; #define G_MMA(ai, bj, At, Bt) do { __builtin_amdgcn_s_setprio(1); _Pragma("unroll") for (int m = 0; m < 4; ++m) _Pragma("unroll") for (int n = 0; n < 2; ++n) _Pragma("unroll") for (int k = 0; k < 2; ++k) \
;     acc[ai][bj][m][n] = __builtin_amdgcn_mfma_f32_16x16x32_bf16(Bt[n][k], At[m][k], acc[ai][bj][m][n], 0, 0, 0); __builtin_amdgcn_s_setprio(0); } while (0)
; #define G_WAIT_V(n) asm volatile("s_waitcnt vmcnt(" #n ")" ::: "memory")
; #define G_WAIT_L(n) asm volatile("s_waitcnt lgkmcnt(" #n ")" ::: "memory")
; #define G_BAR __builtin_amdgcn_s_barrier()
; #define G_SCHED __builtin_amdgcn_sched_barrier(0)
; template <int MODE>
; __device__ __forceinline__ void gemm_epilogue(const Params& p, int layer, const f32x4 (&acc)[2][2][4][2], int pm, int pn, int wr, int wc, int fr, int fq) {
;     ...
;         for (int bj = 0; bj < 2; ++bj) { const int col = pn * 256 + bj * 128 + wc * 32 + 8 * fq;
;           bf16_t* xq = p.XB() + (size_t)row * DM + col; const u32x4 r = *(const u32x4*)xq; const f32x4 a0 = acc[ai][bj][m][0], a1 = acc[ai][bj][m][1];
; template <int MODE>
; __device__ __forceinline__ void gemm_phase(const Params& p, int layer, char* lds_generic) {
;     ...
;       G_BAR; G_WAIT_L(0); G_MMA(1, 0, At, B0); G_BAR; G_SCHED;
;       G_STAGE(G_SB(1, 1), b3 + hstep);
;       G_WAIT_V(6); G_BAR; G_MMA(1, 1, At, B1); G_BAR;
	s_waitcnt lgkmcnt(0)
	v_mfma_f32_16x16x32_bf16 v[60:63], v[134:137], v[154:157], v[60:63]
	v_mfma_f32_16x16x32_bf16 v[56:59], v[146:149], v[154:157], v[56:59]
	v_mfma_f32_16x16x32_bf16 v[44:47], v[134:137], v[162:165], v[44:47]
	v_mfma_f32_16x16x32_bf16 v[40:43], v[146:149], v[162:165], v[40:43]
	v_mfma_f32_16x16x32_bf16 v[28:31], v[134:137], v[170:173], v[28:31]
	v_mfma_f32_16x16x32_bf16 v[24:27], v[146:149], v[170:173], v[24:27]
	v_mfma_f32_16x16x32_bf16 v[12:15], v[134:137], v[178:181], v[12:15]
	v_mfma_f32_16x16x32_bf16 v[8:11], v[146:149], v[178:181], v[8:11]
	v_mfma_f32_16x16x32_bf16 v[60:63], v[142:145], v[158:161], v[60:63]
	v_mfma_f32_16x16x32_bf16 v[56:59], v[150:153], v[158:161], v[56:59]
	v_mfma_f32_16x16x32_bf16 v[44:47], v[142:145], v[166:169], v[44:47]
	v_mfma_f32_16x16x32_bf16 v[40:43], v[150:153], v[166:169], v[40:43]
	v_mfma_f32_16x16x32_bf16 v[28:31], v[142:145], v[174:177], v[28:31]
	v_mfma_f32_16x16x32_bf16 v[24:27], v[150:153], v[174:177], v[24:27]
	v_mfma_f32_16x16x32_bf16 v[12:15], v[142:145], v[182:185], v[12:15]
	v_mfma_f32_16x16x32_bf16 v[8:11], v[150:153], v[182:185], v[8:11]
	s_barrier
	s_add_u32 s66, s76, 0x80080
	s_addc_u32 s67, s77, 0
	s_mov_b32 m0, s85
	v_lshl_add_u64 v[134:135], s[66:67], 0, v[192:193]
	global_load_lds_dwordx4 v[134:135], off
	v_lshl_add_u64 v[134:135], s[66:67], 0, v[128:129]
	s_mov_b32 m0, s80
	s_nop 0
	global_load_lds_dwordx4 v[134:135], off
	s_waitcnt vmcnt(6)
	s_barrier
	v_mfma_f32_16x16x32_bf16 v[52:55], v[186:189], v[154:157], v[52:55]
	v_mfma_f32_16x16x32_bf16 v[48:51], v[198:201], v[154:157], v[48:51]
	v_mfma_f32_16x16x32_bf16 v[36:39], v[186:189], v[162:165], v[36:39]
	v_mfma_f32_16x16x32_bf16 v[32:35], v[198:201], v[162:165], v[32:35]
	v_mfma_f32_16x16x32_bf16 v[20:23], v[186:189], v[170:173], v[20:23]
	v_mfma_f32_16x16x32_bf16 v[16:19], v[198:201], v[170:173], v[16:19]
	v_mfma_f32_16x16x32_bf16 v[4:7], v[186:189], v[178:181], v[4:7]
	v_mfma_f32_16x16x32_bf16 v[0:3], v[198:201], v[178:181], v[0:3]
	v_mfma_f32_16x16x32_bf16 v[52:55], v[194:197], v[158:161], v[52:55]
	v_mfma_f32_16x16x32_bf16 v[48:51], v[202:205], v[158:161], v[48:51]
	v_mfma_f32_16x16x32_bf16 v[36:39], v[194:197], v[166:169], v[36:39]
	v_mfma_f32_16x16x32_bf16 v[32:35], v[202:205], v[166:169], v[32:35]
	v_mfma_f32_16x16x32_bf16 v[20:23], v[194:197], v[174:177], v[20:23]
	v_mfma_f32_16x16x32_bf16 v[16:19], v[202:205], v[174:177], v[16:19]
	v_mfma_f32_16x16x32_bf16 v[4:7], v[194:197], v[182:185], v[4:7]
	v_mfma_f32_16x16x32_bf16 v[0:3], v[202:205], v[182:185], v[0:3]
	s_add_i32 s9, s9, 2
	s_add_u32 vcc_lo, vcc_lo, 0x100
	s_addc_u32 vcc_hi, vcc_hi, 0
	s_add_u32 s89, s89, 0x100
	s_addc_u32 s60, s60, 0
	s_cmp_gt_u32 s9, 29
	s_barrier
	s_cbranch_scc0 .LBB0_103
	v_lshl_add_u32 v134, s62, 8, v138
	v_lshl_or_b32 v136, s63, 8, v141
	v_ashrrev_i32_e32 v135, 31, v134
	v_lshlrev_b64 v[142:143], 12, v[134:135]
	v_ashrrev_i32_e32 v137, 31, v136
	v_lshl_add_u64 v[142:143], s[6:7], 0, v[142:143]
	v_lshlrev_b64 v[136:137], 1, v[136:137]
	v_lshl_add_u64 v[146:147], v[142:143], 0, v[136:137]
	global_load_dwordx4 v[148:151], v[146:147], off
	global_load_dwordx4 v[152:155], v[146:147], off offset:256
	s_mov_b64 s[100:101], 0x10000
	v_lshl_add_u64 v[210:211], v[146:147], 0, s[100:101]
	global_load_dwordx4 v[156:159], v[210:211], off
	global_load_dwordx4 v[160:163], v[210:211], off offset:256
	s_mov_b64 s[100:101], 0x20000
	v_lshl_add_u64 v[210:211], v[146:147], 0, s[100:101]
	global_load_dwordx4 v[164:167], v[210:211], off
	global_load_dwordx4 v[168:171], v[210:211], off offset:256
	s_mov_b64 s[100:101], 0x30000
	v_lshl_add_u64 v[210:211], v[146:147], 0, s[100:101]
	global_load_dwordx4 v[172:175], v[210:211], off
	global_load_dwordx4 v[176:179], v[210:211], off offset:256
	s_mov_b64 s[100:101], 0x80000
	v_lshl_add_u64 v[210:211], v[146:147], 0, s[100:101]
	global_load_dwordx4 v[180:183], v[210:211], off
	global_load_dwordx4 v[184:187], v[210:211], off offset:256
	s_mov_b64 s[100:101], 0x90000
	v_lshl_add_u64 v[210:211], v[146:147], 0, s[100:101]
	global_load_dwordx4 v[194:197], v[210:211], off
	global_load_dwordx4 v[198:201], v[210:211], off offset:256
	s_mov_b64 s[100:101], 0xa0000
	v_lshl_add_u64 v[210:211], v[146:147], 0, s[100:101]
	global_load_dwordx4 v[202:205], v[210:211], off
	global_load_dwordx4 v[206:209], v[210:211], off offset:256
	s_mov_b64 s[100:101], 0xb0000
	v_lshl_add_u64 v[210:211], v[146:147], 0, s[100:101]
	global_load_dwordx4 v[216:219], v[210:211], off
	global_load_dwordx4 v[222:225], v[210:211], off offset:256
	s_and_b64 vcc, exec, s[72:73]
	s_mov_b32 s62, s68
	s_mov_b32 s63, s70
	s_mov_b64 s[78:79], s[74:75]
	s_mov_b64 s[76:77], s[86:87]
	s_waitcnt vmcnt(0)
;   __device__ __forceinline__ bf16_t* XB() const { return (bf16_t*)(ws + 328 * MB); }
; __device__ __forceinline__ float bflo(unsigned w) { return __uint_as_float(w << 16); }
; __device__ __forceinline__ float bfhi(unsigned w) { return __uint_as_float(w & 0xffff0000u); }
; template <int MODE>
; __device__ __forceinline__ void gemm_epilogue(const Params& p, int layer, const f32x4 (&acc)[2][2][4][2], int pm, int pn, int wr, int wc, int fr, int fq) {
;     ...
;         for (int bj = 0; bj < 2; ++bj) { const int col = pn * 256 + bj * 128 + wc * 32 + 8 * fq;
;           bf16_t* xq = p.XB() + (size_t)row * DM + col; const u32x4 r = *(const u32x4*)xq; const f32x4 a0 = acc[ai][bj][m][0], a1 = acc[ai][bj][m][1];
;           const u32x4 w = {cvtpk(a0[0] + bflo(r[0]), a0[1] + bfhi(r[0])), cvtpk(a0[2] + bflo(r[1]), a0[3] + bfhi(r[1])), cvtpk(a1[0] + bflo(r[2]), a1[1] + bfhi(r[2])), cvtpk(a1[2] + bflo(r[3]), a1[3] + bfhi(r[3]))};
;           *(u32x4*)xq = w; }
	v_mov_b64_e32 v[142:143], v[148:149]
	v_mov_b64_e32 v[144:145], v[150:151]
	v_lshlrev_b32_e32 v135, 16, v142
	v_add_f32_e32 v124, v124, v135
	v_and_b32_e32 v135, 0xffff0000, v142
	v_add_f32_e32 v125, v125, v135
	v_cvt_pk_bf16_f32 v124, v124, v125
	v_lshlrev_b32_e32 v125, 16, v143
	v_add_f32_e32 v125, v126, v125
	v_and_b32_e32 v126, 0xffff0000, v143
	v_add_f32_e32 v126, v127, v126
	v_cvt_pk_bf16_f32 v125, v125, v126
	v_lshlrev_b32_e32 v126, 16, v144
	v_add_f32_e32 v120, v120, v126
	v_and_b32_e32 v126, 0xffff0000, v144
	v_add_f32_e32 v121, v121, v126
	v_cvt_pk_bf16_f32 v126, v120, v121
	v_lshlrev_b32_e32 v120, 16, v145
	v_and_b32_e32 v121, 0xffff0000, v145
	v_add_f32_e32 v120, v122, v120
	v_add_f32_e32 v121, v123, v121
	v_cvt_pk_bf16_f32 v127, v120, v121
	v_mov_b64_e32 v[120:121], v[152:153]
	v_mov_b64_e32 v[122:123], v[154:155]
	s_nop 0
	global_store_dwordx4 v[146:147], v[124:127], off
	s_nop 0
	v_lshlrev_b32_e32 v124, 16, v120
	v_and_b32_e32 v120, 0xffff0000, v120
	v_add_f32_e32 v116, v116, v124
	v_add_f32_e32 v117, v117, v120
	v_cvt_pk_bf16_f32 v116, v116, v117
	v_lshlrev_b32_e32 v117, 16, v121
	v_add_f32_e32 v117, v118, v117
	v_and_b32_e32 v118, 0xffff0000, v121
	v_add_f32_e32 v118, v119, v118
	v_cvt_pk_bf16_f32 v117, v117, v118
	v_lshlrev_b32_e32 v118, 16, v122
	v_add_f32_e32 v112, v112, v118
	v_and_b32_e32 v118, 0xffff0000, v122
	v_add_f32_e32 v113, v113, v118
	v_cvt_pk_bf16_f32 v118, v112, v113
	v_lshlrev_b32_e32 v112, 16, v123
	v_add_f32_e32 v112, v114, v112
	v_and_b32_e32 v113, 0xffff0000, v123
	v_add_f32_e32 v113, v115, v113
	v_cvt_pk_bf16_f32 v119, v112, v113
	v_or_b32_e32 v112, 16, v134
	v_ashrrev_i32_e32 v113, 31, v112
	v_lshlrev_b64 v[112:113], 12, v[112:113]
	v_lshl_add_u64 v[112:113], s[6:7], 0, v[112:113]
	global_store_dwordx4 v[146:147], v[116:119], off offset:256
	s_nop 1
	v_lshl_add_u64 v[116:117], v[112:113], 0, v[136:137]
	v_mov_b64_e32 v[112:113], v[156:157]
	v_mov_b64_e32 v[114:115], v[158:159]
	v_lshlrev_b32_e32 v118, 16, v112
	v_and_b32_e32 v112, 0xffff0000, v112
	v_add_f32_e32 v108, v108, v118
	v_add_f32_e32 v109, v109, v112
	v_cvt_pk_bf16_f32 v108, v108, v109
	v_lshlrev_b32_e32 v109, 16, v113
	v_add_f32_e32 v109, v110, v109
	v_and_b32_e32 v110, 0xffff0000, v113
	v_add_f32_e32 v110, v111, v110
	v_cvt_pk_bf16_f32 v109, v109, v110
	v_lshlrev_b32_e32 v110, 16, v114
	v_add_f32_e32 v104, v104, v110
	v_and_b32_e32 v110, 0xffff0000, v114
	v_add_f32_e32 v105, v105, v110
	v_cvt_pk_bf16_f32 v110, v104, v105
	v_lshlrev_b32_e32 v104, 16, v115
	v_and_b32_e32 v105, 0xffff0000, v115
	v_add_f32_e32 v104, v106, v104
	v_add_f32_e32 v105, v107, v105
	v_cvt_pk_bf16_f32 v111, v104, v105
	v_mov_b64_e32 v[104:105], v[160:161]
	v_mov_b64_e32 v[106:107], v[162:163]
	s_nop 0
	global_store_dwordx4 v[116:117], v[108:111], off
	s_nop 0
	v_lshlrev_b32_e32 v108, 16, v104
	v_and_b32_e32 v104, 0xffff0000, v104
	v_add_f32_e32 v100, v100, v108
	v_add_f32_e32 v101, v101, v104
	v_cvt_pk_bf16_f32 v100, v100, v101
	v_lshlrev_b32_e32 v101, 16, v105
	v_add_f32_e32 v101, v102, v101
	v_and_b32_e32 v102, 0xffff0000, v105
	v_add_f32_e32 v102, v103, v102
	v_cvt_pk_bf16_f32 v101, v101, v102
	v_lshlrev_b32_e32 v102, 16, v106
	v_add_f32_e32 v96, v96, v102
	v_and_b32_e32 v102, 0xffff0000, v106
	v_add_f32_e32 v97, v97, v102
	v_cvt_pk_bf16_f32 v102, v96, v97
	v_lshlrev_b32_e32 v96, 16, v107
	v_add_f32_e32 v96, v98, v96
	v_and_b32_e32 v97, 0xffff0000, v107
	v_add_f32_e32 v97, v99, v97
	v_cvt_pk_bf16_f32 v103, v96, v97
	v_or_b32_e32 v96, 32, v134
	v_ashrrev_i32_e32 v97, 31, v96
	v_lshlrev_b64 v[96:97], 12, v[96:97]
	v_lshl_add_u64 v[96:97], s[6:7], 0, v[96:97]
	global_store_dwordx4 v[116:117], v[100:103], off offset:256
	s_nop 1
	v_lshl_add_u64 v[100:101], v[96:97], 0, v[136:137]
	v_mov_b64_e32 v[96:97], v[164:165]
	v_mov_b64_e32 v[98:99], v[166:167]
	v_lshlrev_b32_e32 v102, 16, v96
	v_and_b32_e32 v96, 0xffff0000, v96
	v_add_f32_e32 v92, v92, v102
	v_add_f32_e32 v93, v93, v96
	v_cvt_pk_bf16_f32 v92, v92, v93
	v_lshlrev_b32_e32 v93, 16, v97
	v_add_f32_e32 v93, v94, v93
	v_and_b32_e32 v94, 0xffff0000, v97
	v_add_f32_e32 v94, v95, v94
	v_cvt_pk_bf16_f32 v93, v93, v94
	v_lshlrev_b32_e32 v94, 16, v98
	v_add_f32_e32 v88, v88, v94
	v_and_b32_e32 v94, 0xffff0000, v98
	v_add_f32_e32 v89, v89, v94
	v_cvt_pk_bf16_f32 v94, v88, v89
	v_lshlrev_b32_e32 v88, 16, v99
	v_and_b32_e32 v89, 0xffff0000, v99
	v_add_f32_e32 v88, v90, v88
	v_add_f32_e32 v89, v91, v89
	v_cvt_pk_bf16_f32 v95, v88, v89
	v_mov_b64_e32 v[88:89], v[168:169]
	v_mov_b64_e32 v[90:91], v[170:171]
	s_nop 0
	global_store_dwordx4 v[100:101], v[92:95], off
	s_nop 0
	v_lshlrev_b32_e32 v92, 16, v88
	v_and_b32_e32 v88, 0xffff0000, v88
	v_add_f32_e32 v84, v84, v92
	v_add_f32_e32 v85, v85, v88
	v_cvt_pk_bf16_f32 v84, v84, v85
	v_lshlrev_b32_e32 v85, 16, v89
	v_add_f32_e32 v85, v86, v85
	v_and_b32_e32 v86, 0xffff0000, v89
	v_add_f32_e32 v86, v87, v86
	v_cvt_pk_bf16_f32 v85, v85, v86
	v_lshlrev_b32_e32 v86, 16, v90
	v_add_f32_e32 v80, v80, v86
	v_and_b32_e32 v86, 0xffff0000, v90
	v_add_f32_e32 v81, v81, v86
	v_cvt_pk_bf16_f32 v86, v80, v81
	v_lshlrev_b32_e32 v80, 16, v91
	v_add_f32_e32 v80, v82, v80
	v_and_b32_e32 v81, 0xffff0000, v91
	v_add_f32_e32 v81, v83, v81
	v_cvt_pk_bf16_f32 v87, v80, v81
	v_or_b32_e32 v80, 48, v134
	v_ashrrev_i32_e32 v81, 31, v80
	v_lshlrev_b64 v[80:81], 12, v[80:81]
	v_lshl_add_u64 v[80:81], s[6:7], 0, v[80:81]
	global_store_dwordx4 v[100:101], v[84:87], off offset:256
	s_nop 1
	v_lshl_add_u64 v[84:85], v[80:81], 0, v[136:137]
	v_mov_b64_e32 v[80:81], v[172:173]
	v_mov_b64_e32 v[82:83], v[174:175]
	v_lshlrev_b32_e32 v86, 16, v80
	v_and_b32_e32 v80, 0xffff0000, v80
	v_add_f32_e32 v76, v76, v86
;   __device__ __forceinline__ bf16_t* XB() const { return (bf16_t*)(ws + 328 * MB); }
; __device__ __forceinline__ float bflo(unsigned w) { return __uint_as_float(w << 16); }
; __device__ __forceinline__ float bfhi(unsigned w) { return __uint_as_float(w & 0xffff0000u); }
; template <int MODE>
; __device__ __forceinline__ void gemm_epilogue(const Params& p, int layer, const f32x4 (&acc)[2][2][4][2], int pm, int pn, int wr, int wc, int fr, int fq) {
;     ...
;         for (int bj = 0; bj < 2; ++bj) { const int col = pn * 256 + bj * 128 + wc * 32 + 8 * fq;
;           bf16_t* xq = p.XB() + (size_t)row * DM + col; const u32x4 r = *(const u32x4*)xq; const f32x4 a0 = acc[ai][bj][m][0], a1 = acc[ai][bj][m][1];
;           const u32x4 w = {cvtpk(a0[0] + bflo(r[0]), a0[1] + bfhi(r[0])), cvtpk(a0[2] + bflo(r[1]), a0[3] + bfhi(r[1])), cvtpk(a1[0] + bflo(r[2]), a1[1] + bfhi(r[2])), cvtpk(a1[2] + bflo(r[3]), a1[3] + bfhi(r[3]))};
;           *(u32x4*)xq = w; }
	v_add_f32_e32 v77, v77, v80
	v_cvt_pk_bf16_f32 v76, v76, v77
	v_lshlrev_b32_e32 v77, 16, v81
	v_add_f32_e32 v77, v78, v77
	v_and_b32_e32 v78, 0xffff0000, v81
	v_add_f32_e32 v78, v79, v78
	v_cvt_pk_bf16_f32 v77, v77, v78
	v_lshlrev_b32_e32 v78, 16, v82
	v_add_f32_e32 v72, v72, v78
	v_and_b32_e32 v78, 0xffff0000, v82
	v_add_f32_e32 v73, v73, v78
	v_cvt_pk_bf16_f32 v78, v72, v73
	v_lshlrev_b32_e32 v72, 16, v83
	v_and_b32_e32 v73, 0xffff0000, v83
	v_add_f32_e32 v72, v74, v72
	v_add_f32_e32 v73, v75, v73
	v_cvt_pk_bf16_f32 v79, v72, v73
	v_mov_b64_e32 v[72:73], v[176:177]
	v_mov_b64_e32 v[74:75], v[178:179]
	s_nop 0
	global_store_dwordx4 v[84:85], v[76:79], off
	s_nop 0
	v_lshlrev_b32_e32 v76, 16, v72
	v_and_b32_e32 v72, 0xffff0000, v72
	v_add_f32_e32 v68, v68, v76
	v_add_f32_e32 v69, v69, v72
	v_cvt_pk_bf16_f32 v68, v68, v69
	v_lshlrev_b32_e32 v69, 16, v73
	v_add_f32_e32 v69, v70, v69
	v_and_b32_e32 v70, 0xffff0000, v73
	v_add_f32_e32 v70, v71, v70
	v_cvt_pk_bf16_f32 v69, v69, v70
	v_lshlrev_b32_e32 v70, 16, v74
	v_add_f32_e32 v64, v64, v70
	v_and_b32_e32 v70, 0xffff0000, v74
	v_add_f32_e32 v65, v65, v70
	v_cvt_pk_bf16_f32 v70, v64, v65
	v_lshlrev_b32_e32 v64, 16, v75
	v_add_f32_e32 v64, v66, v64
	v_and_b32_e32 v65, 0xffff0000, v75
	v_add_f32_e32 v65, v67, v65
	v_cvt_pk_bf16_f32 v71, v64, v65
	v_add_u32_e32 v64, 0x80, v134
	v_ashrrev_i32_e32 v65, 31, v64
	v_lshlrev_b64 v[64:65], 12, v[64:65]
	v_lshl_add_u64 v[64:65], s[6:7], 0, v[64:65]
	global_store_dwordx4 v[84:85], v[68:71], off offset:256
	s_nop 1
	v_lshl_add_u64 v[68:69], v[64:65], 0, v[136:137]
	v_mov_b64_e32 v[64:65], v[180:181]
	v_mov_b64_e32 v[66:67], v[182:183]
	v_lshlrev_b32_e32 v70, 16, v64
	v_and_b32_e32 v64, 0xffff0000, v64
	v_add_f32_e32 v60, v60, v70
	v_add_f32_e32 v61, v61, v64
	v_cvt_pk_bf16_f32 v60, v60, v61
	v_lshlrev_b32_e32 v61, 16, v65
	v_add_f32_e32 v61, v62, v61
	v_and_b32_e32 v62, 0xffff0000, v65
	v_add_f32_e32 v62, v63, v62
	v_cvt_pk_bf16_f32 v61, v61, v62
	v_lshlrev_b32_e32 v62, 16, v66
	v_add_f32_e32 v56, v56, v62
	v_and_b32_e32 v62, 0xffff0000, v66
	v_add_f32_e32 v57, v57, v62
	v_cvt_pk_bf16_f32 v62, v56, v57
	v_lshlrev_b32_e32 v56, 16, v67
	v_and_b32_e32 v57, 0xffff0000, v67
	v_add_f32_e32 v56, v58, v56
	v_add_f32_e32 v57, v59, v57
	v_cvt_pk_bf16_f32 v63, v56, v57
	v_mov_b64_e32 v[56:57], v[184:185]
	v_mov_b64_e32 v[58:59], v[186:187]
	s_nop 0
	global_store_dwordx4 v[68:69], v[60:63], off
	s_nop 0
	v_lshlrev_b32_e32 v60, 16, v56
	v_and_b32_e32 v56, 0xffff0000, v56
	v_add_f32_e32 v52, v52, v60
	v_add_f32_e32 v53, v53, v56
	v_cvt_pk_bf16_f32 v52, v52, v53
	v_lshlrev_b32_e32 v53, 16, v57
	v_add_f32_e32 v53, v54, v53
	v_and_b32_e32 v54, 0xffff0000, v57
	v_add_f32_e32 v54, v55, v54
	v_cvt_pk_bf16_f32 v53, v53, v54
	v_lshlrev_b32_e32 v54, 16, v58
	v_add_f32_e32 v48, v48, v54
	v_and_b32_e32 v54, 0xffff0000, v58
	v_add_f32_e32 v49, v49, v54
	v_cvt_pk_bf16_f32 v54, v48, v49
	v_lshlrev_b32_e32 v48, 16, v59
	v_add_f32_e32 v48, v50, v48
	v_and_b32_e32 v49, 0xffff0000, v59
	v_add_f32_e32 v49, v51, v49
	v_cvt_pk_bf16_f32 v55, v48, v49
	v_add_u32_e32 v48, 0x90, v134
	v_ashrrev_i32_e32 v49, 31, v48
	v_lshlrev_b64 v[48:49], 12, v[48:49]
	v_lshl_add_u64 v[48:49], s[6:7], 0, v[48:49]
	global_store_dwordx4 v[68:69], v[52:55], off offset:256
	s_nop 1
	v_lshl_add_u64 v[52:53], v[48:49], 0, v[136:137]
	v_mov_b64_e32 v[48:49], v[194:195]
	v_mov_b64_e32 v[50:51], v[196:197]
	v_lshlrev_b32_e32 v54, 16, v48
	v_and_b32_e32 v48, 0xffff0000, v48
	v_add_f32_e32 v44, v44, v54
	v_add_f32_e32 v45, v45, v48
	v_cvt_pk_bf16_f32 v44, v44, v45
	v_lshlrev_b32_e32 v45, 16, v49
	v_add_f32_e32 v45, v46, v45
	v_and_b32_e32 v46, 0xffff0000, v49
	v_add_f32_e32 v46, v47, v46
	v_cvt_pk_bf16_f32 v45, v45, v46
	v_lshlrev_b32_e32 v46, 16, v50
	v_add_f32_e32 v40, v40, v46
	v_and_b32_e32 v46, 0xffff0000, v50
	v_add_f32_e32 v41, v41, v46
	v_cvt_pk_bf16_f32 v46, v40, v41
	v_lshlrev_b32_e32 v40, 16, v51
	v_and_b32_e32 v41, 0xffff0000, v51
	v_add_f32_e32 v40, v42, v40
	v_add_f32_e32 v41, v43, v41
	v_cvt_pk_bf16_f32 v47, v40, v41
	v_mov_b64_e32 v[40:41], v[198:199]
	v_mov_b64_e32 v[42:43], v[200:201]
	s_nop 0
	global_store_dwordx4 v[52:53], v[44:47], off
	s_nop 0
	v_lshlrev_b32_e32 v44, 16, v40
	v_and_b32_e32 v40, 0xffff0000, v40
	v_add_f32_e32 v36, v36, v44
;   __device__ __forceinline__ bf16_t* XB() const { return (bf16_t*)(ws + 328 * MB); }
; __device__ __forceinline__ float bflo(unsigned w) { return __uint_as_float(w << 16); }
; __device__ __forceinline__ float bfhi(unsigned w) { return __uint_as_float(w & 0xffff0000u); }
; #define G_WAIT_V(n) asm volatile("s_waitcnt vmcnt(" #n ")" ::: "memory")
; #define G_BAR __builtin_amdgcn_s_barrier()
; template <int MODE>
; __device__ __forceinline__ void gemm_epilogue(const Params& p, int layer, const f32x4 (&acc)[2][2][4][2], int pm, int pn, int wr, int wc, int fr, int fq) {
;     ...
;         for (int bj = 0; bj < 2; ++bj) { const int col = pn * 256 + bj * 128 + wc * 32 + 8 * fq;
;           bf16_t* xq = p.XB() + (size_t)row * DM + col; const u32x4 r = *(const u32x4*)xq; const f32x4 a0 = acc[ai][bj][m][0], a1 = acc[ai][bj][m][1];
;           const u32x4 w = {cvtpk(a0[0] + bflo(r[0]), a0[1] + bfhi(r[0])), cvtpk(a0[2] + bflo(r[1]), a0[3] + bfhi(r[1])), cvtpk(a1[0] + bflo(r[2]), a1[1] + bfhi(r[2])), cvtpk(a1[2] + bflo(r[3]), a1[3] + bfhi(r[3]))};
;           *(u32x4*)xq = w; }
; template <int MODE>
; __device__ __forceinline__ void gemm_phase(const Params& p, int layer, char* lds_generic) {
;     ...
;     if (!has_next) break;
; #pragma unroll
;     for (int a = 0; a < 2; ++a)
; #pragma unroll
;       for (int b = 0; b < 2; ++b)
; #pragma unroll
;         for (int m = 0; m < 4; ++m)
; #pragma unroll
;           for (int n = 0; n < 2; ++n) acc[a][b][m][n] = (f32x4){0.f, 0.f, 0.f, 0.f};
;     cpm = npm; cpn = npn; cA = nA; cB = nB; ++ui;
;   }
;   G_WAIT_V(0);
;   if (wr == 0) G_BAR;
;   G_BAR;
	v_add_f32_e32 v37, v37, v40
	v_cvt_pk_bf16_f32 v36, v36, v37
	v_lshlrev_b32_e32 v37, 16, v41
	v_add_f32_e32 v37, v38, v37
	v_and_b32_e32 v38, 0xffff0000, v41
	v_add_f32_e32 v38, v39, v38
	v_cvt_pk_bf16_f32 v37, v37, v38
	v_lshlrev_b32_e32 v38, 16, v42
	v_add_f32_e32 v32, v32, v38
	v_and_b32_e32 v38, 0xffff0000, v42
	v_add_f32_e32 v33, v33, v38
	v_cvt_pk_bf16_f32 v38, v32, v33
	v_lshlrev_b32_e32 v32, 16, v43
	v_add_f32_e32 v32, v34, v32
	v_and_b32_e32 v33, 0xffff0000, v43
	v_add_f32_e32 v33, v35, v33
	v_cvt_pk_bf16_f32 v39, v32, v33
	v_add_u32_e32 v32, 0xa0, v134
	v_ashrrev_i32_e32 v33, 31, v32
	v_lshlrev_b64 v[32:33], 12, v[32:33]
	v_lshl_add_u64 v[32:33], s[6:7], 0, v[32:33]
	global_store_dwordx4 v[52:53], v[36:39], off offset:256
	s_nop 1
	v_lshl_add_u64 v[36:37], v[32:33], 0, v[136:137]
	v_mov_b64_e32 v[32:33], v[202:203]
	v_mov_b64_e32 v[34:35], v[204:205]
	v_lshlrev_b32_e32 v38, 16, v32
	v_and_b32_e32 v32, 0xffff0000, v32
	v_add_f32_e32 v28, v28, v38
	v_add_f32_e32 v29, v29, v32
	v_cvt_pk_bf16_f32 v28, v28, v29
	v_lshlrev_b32_e32 v29, 16, v33
	v_add_f32_e32 v29, v30, v29
	v_and_b32_e32 v30, 0xffff0000, v33
	v_add_f32_e32 v30, v31, v30
	v_cvt_pk_bf16_f32 v29, v29, v30
	v_lshlrev_b32_e32 v30, 16, v34
	v_add_f32_e32 v24, v24, v30
	v_and_b32_e32 v30, 0xffff0000, v34
	v_add_f32_e32 v25, v25, v30
	v_cvt_pk_bf16_f32 v30, v24, v25
	v_lshlrev_b32_e32 v24, 16, v35
	v_and_b32_e32 v25, 0xffff0000, v35
	v_add_f32_e32 v24, v26, v24
	v_add_f32_e32 v25, v27, v25
	v_cvt_pk_bf16_f32 v31, v24, v25
	v_mov_b64_e32 v[24:25], v[206:207]
	v_mov_b64_e32 v[26:27], v[208:209]
	s_nop 0
	global_store_dwordx4 v[36:37], v[28:31], off
	s_nop 0
	v_lshlrev_b32_e32 v28, 16, v24
	v_and_b32_e32 v24, 0xffff0000, v24
	v_add_f32_e32 v20, v20, v28
	v_add_f32_e32 v21, v21, v24
	v_cvt_pk_bf16_f32 v20, v20, v21
	v_lshlrev_b32_e32 v21, 16, v25
	v_add_f32_e32 v21, v22, v21
	v_and_b32_e32 v22, 0xffff0000, v25
	v_add_f32_e32 v22, v23, v22
	v_cvt_pk_bf16_f32 v21, v21, v22
	v_lshlrev_b32_e32 v22, 16, v26
	v_add_f32_e32 v16, v16, v22
	v_and_b32_e32 v22, 0xffff0000, v26
	v_add_f32_e32 v17, v17, v22
	v_cvt_pk_bf16_f32 v22, v16, v17
	v_lshlrev_b32_e32 v16, 16, v27
	v_add_f32_e32 v16, v18, v16
	v_and_b32_e32 v17, 0xffff0000, v27
	v_add_f32_e32 v17, v19, v17
	v_cvt_pk_bf16_f32 v23, v16, v17
	v_add_u32_e32 v16, 0xb0, v134
	v_ashrrev_i32_e32 v17, 31, v16
	v_lshlrev_b64 v[16:17], 12, v[16:17]
	v_lshl_add_u64 v[16:17], s[6:7], 0, v[16:17]
	global_store_dwordx4 v[36:37], v[20:23], off offset:256
	s_nop 1
	v_lshl_add_u64 v[20:21], v[16:17], 0, v[136:137]
	v_mov_b64_e32 v[16:17], v[216:217]
	v_mov_b64_e32 v[18:19], v[218:219]
	v_lshlrev_b32_e32 v22, 16, v16
	v_and_b32_e32 v16, 0xffff0000, v16
	v_add_f32_e32 v12, v12, v22
	v_add_f32_e32 v13, v13, v16
	v_cvt_pk_bf16_f32 v12, v12, v13
	v_lshlrev_b32_e32 v13, 16, v17
	v_add_f32_e32 v13, v14, v13
	v_and_b32_e32 v14, 0xffff0000, v17
	v_add_f32_e32 v14, v15, v14
	v_cvt_pk_bf16_f32 v13, v13, v14
	v_lshlrev_b32_e32 v14, 16, v18
	v_add_f32_e32 v8, v8, v14
	v_and_b32_e32 v14, 0xffff0000, v18
	v_add_f32_e32 v9, v9, v14
	v_cvt_pk_bf16_f32 v14, v8, v9
	v_lshlrev_b32_e32 v8, 16, v19
	v_and_b32_e32 v9, 0xffff0000, v19
	v_add_f32_e32 v8, v10, v8
	v_add_f32_e32 v9, v11, v9
	v_cvt_pk_bf16_f32 v15, v8, v9
	v_mov_b64_e32 v[8:9], v[222:223]
	v_mov_b64_e32 v[10:11], v[224:225]
	s_nop 0
	global_store_dwordx4 v[20:21], v[12:15], off
	s_nop 0
	v_lshlrev_b32_e32 v12, 16, v8
	v_and_b32_e32 v8, 0xffff0000, v8
	v_add_f32_e32 v4, v4, v12
	v_add_f32_e32 v5, v5, v8
	v_cvt_pk_bf16_f32 v4, v4, v5
	v_lshlrev_b32_e32 v5, 16, v9
	v_add_f32_e32 v5, v6, v5
	v_and_b32_e32 v6, 0xffff0000, v9
	v_add_f32_e32 v6, v7, v6
	v_cvt_pk_bf16_f32 v5, v5, v6
	v_lshlrev_b32_e32 v6, 16, v10
	v_add_f32_e32 v0, v0, v6
	v_and_b32_e32 v6, 0xffff0000, v10
	v_add_f32_e32 v1, v1, v6
	v_cvt_pk_bf16_f32 v6, v0, v1
	v_lshlrev_b32_e32 v0, 16, v11
	v_and_b32_e32 v1, 0xffff0000, v11
	v_add_f32_e32 v0, v2, v0
	v_add_f32_e32 v1, v3, v1
	v_cvt_pk_bf16_f32 v7, v0, v1
	global_store_dwordx4 v[20:21], v[4:7], off offset:256
	s_cbranch_vccz .LBB0_100
	s_waitcnt vmcnt(0)
	v_readlane_b32 s82, v254, 24
	s_cmpk_gt_u32 s15, 0xff
	v_readlane_b32 s83, v254, 25
	s_mov_b64 s[84:85], s[16:17]
	v_readlane_b32 s63, v254, 27
	s_cbranch_scc1 .LBB0_107
	s_barrier

; #define G_STAGE(bufoff, gbase) do { _Pragma("unroll") for (int _i = 0; _i < 2; ++_i) \
;     __builtin_amdgcn_global_load_lds((const unsigned*)((const char*)(gbase) + voffA[_i]), (LAS unsigned*)(lds + (bufoff) + ldsw + _i * 8192), 16, 0, 0); } while (0)
; #define G_LDA(dst, b, h) do { _Pragma("unroll") for (int m = 0; m < 4; ++m) _Pragma("unroll") for (int k = 0; k < 2; ++k) dst[m][k] = *(const LAS bf16x8*)(lds + G_SA(b, h) + aoff + m * 2048 + k * 1024); } while (0)
; #define G_LDB(dst, b, h) do { _Pragma("unroll") for (int n = 0; n < 2; ++n) _Pragma("unroll") for (int k = 0; k < 2; ++k) dst[n][k] = *(const LAS bf16x8*)(lds + G_SB(b, h) + boff + n * 2048 + k * 1024); } while (0)
; #define G_MMA(ai, bj, At, Bt) do { __builtin_amdgcn_s_setprio(1); _Pragma("unroll") for (int m = 0; m < 4; ++m) _Pragma("unroll") for (int n = 0; n < 2; ++n) _Pragma("unroll") for (int k = 0; k < 2; ++k) \
;     acc[ai][bj][m][n] = __builtin_amdgcn_mfma_f32_16x16x32_bf16(Bt[n][k], At[m][k], acc[ai][bj][m][n], 0, 0, 0); __builtin_amdgcn_s_setprio(0); } while (0)
; #define G_WAIT_L(n) asm volatile("s_waitcnt lgkmcnt(" #n ")" ::: "memory")
; #define G_BAR __builtin_amdgcn_s_barrier()
; #define G_SCHED __builtin_amdgcn_sched_barrier(0)
; template <int MODE>
; __device__ __forceinline__ void gemm_phase(const Params& p, int layer, char* lds_generic) {
;     ...
;       G_LDB(B0, 0, 0); G_SCHED; G_LDA(At, 0, 0); G_STAGE(G_SA(1, 1), a1 + hstep);
;       G_WAIT_L(8); G_BAR; G_WAIT_L(0); G_MMA(0, 0, At, B0); G_BAR; G_SCHED;
;       G_LDB(B1, 0, 1); G_STAGE(G_SB(0, 0), b2);
;       G_BAR; G_WAIT_L(0); G_MMA(0, 1, At, B1); G_BAR;
;       G_LDA(At, 0, 1); G_STAGE(G_SA(0, 0), a2);
;       G_BAR; G_WAIT_L(0); G_MMA(1, 0, At, B0); G_BAR; G_SCHED;
.LBB0_196:
	v_or_b32_e32 v128, 0x10000, v152
	v_add_u32_e32 v132, 0x10400, v152
	v_add_u32_e32 v136, 0x10800, v152
	ds_read_b128 v[128:131], v128
	ds_read_b128 v[132:135], v132
	v_add_u32_e32 v137, 0x10c00, v152
	ds_read_b128 v[146:149], v136
	ds_read_b128 v[154:157], v137
	s_add_u32 s6, s4, 0xfff80080
	s_addc_u32 s7, s5, -1
	s_cmp_eq_u32 s47, 28
	s_cselect_b32 s9, s2, s7
	s_cselect_b32 s8, s21, s6
	s_cselect_b32 s7, s23, s46
	s_cselect_b32 s6, s34, s35
	v_lshl_add_u64 v[136:137], s[4:5], 0, v[142:143]
	s_add_i32 m0, s68, 0xc000
	ds_read_b128 v[158:161], v151
	ds_read_b128 v[162:165], v151 offset:1024
	ds_read_b128 v[166:169], v151 offset:2048
	ds_read_b128 v[170:173], v151 offset:3072
	ds_read_b128 v[174:177], v151 offset:4096
	ds_read_b128 v[178:181], v151 offset:5120
	ds_read_b128 v[182:185], v151 offset:6144
	ds_read_b128 v[186:189], v151 offset:7168
	global_load_lds_dwordx4 v[136:137], off
	v_lshl_add_u64 v[136:137], s[4:5], 0, v[144:145]
	s_add_i32 m0, s68, 0xe000
	s_nop 0
	global_load_lds_dwordx4 v[136:137], off
	s_waitcnt lgkmcnt(8)
	s_barrier
	s_waitcnt lgkmcnt(0)
	v_mfma_f32_16x16x32_bf16 v[124:127], v[128:131], v[158:161], v[124:127]
	v_mfma_f32_16x16x32_bf16 v[120:123], v[146:149], v[158:161], v[120:123]
	v_mfma_f32_16x16x32_bf16 v[108:111], v[128:131], v[166:169], v[108:111]
	v_mfma_f32_16x16x32_bf16 v[104:107], v[146:149], v[166:169], v[104:107]
	v_mfma_f32_16x16x32_bf16 v[92:95], v[128:131], v[174:177], v[92:95]
	v_mfma_f32_16x16x32_bf16 v[88:91], v[146:149], v[174:177], v[88:91]
	v_mfma_f32_16x16x32_bf16 v[76:79], v[128:131], v[182:185], v[76:79]
	v_mfma_f32_16x16x32_bf16 v[72:75], v[146:149], v[182:185], v[72:75]
	v_mfma_f32_16x16x32_bf16 v[124:127], v[132:135], v[162:165], v[124:127]
	v_mfma_f32_16x16x32_bf16 v[120:123], v[154:157], v[162:165], v[120:123]
	v_mfma_f32_16x16x32_bf16 v[108:111], v[132:135], v[170:173], v[108:111]
	v_mfma_f32_16x16x32_bf16 v[104:107], v[154:157], v[170:173], v[104:107]
	v_mfma_f32_16x16x32_bf16 v[92:95], v[132:135], v[178:181], v[92:95]
	v_mfma_f32_16x16x32_bf16 v[88:91], v[154:157], v[178:181], v[88:91]
	v_mfma_f32_16x16x32_bf16 v[76:79], v[132:135], v[186:189], v[76:79]
	v_mfma_f32_16x16x32_bf16 v[72:75], v[154:157], v[186:189], v[72:75]
	s_barrier
	v_or_b32_e32 v136, 0x14000, v152
	v_add_u32_e32 v137, 0x14400, v152
	ds_read_b128 v[194:197], v136
	ds_read_b128 v[198:201], v137
	v_add_u32_e32 v136, 0x14800, v152
	v_add_u32_e32 v137, 0x14c00, v152
	s_mov_b32 m0, s69
	ds_read_b128 v[202:205], v136
	ds_read_b128 v[228:231], v137
	v_lshl_add_u64 v[136:137], s[6:7], 0, v[140:141]
	global_load_lds_dwordx4 v[136:137], off
	v_lshl_add_u64 v[190:191], s[6:7], 0, v[138:139]
	s_mov_b32 m0, s70
	s_nop 0
	global_load_lds_dwordx4 v[190:191], off
	s_barrier
	s_waitcnt lgkmcnt(0)
	v_mfma_f32_16x16x32_bf16 v[116:119], v[194:197], v[158:161], v[116:119]
	v_mfma_f32_16x16x32_bf16 v[112:115], v[202:205], v[158:161], v[112:115]
	v_mfma_f32_16x16x32_bf16 v[100:103], v[194:197], v[166:169], v[100:103]
	v_mfma_f32_16x16x32_bf16 v[96:99], v[202:205], v[166:169], v[96:99]
	v_mfma_f32_16x16x32_bf16 v[84:87], v[194:197], v[174:177], v[84:87]
	v_mfma_f32_16x16x32_bf16 v[80:83], v[202:205], v[174:177], v[80:83]
	v_mfma_f32_16x16x32_bf16 v[68:71], v[194:197], v[182:185], v[68:71]
	v_mfma_f32_16x16x32_bf16 v[64:67], v[202:205], v[182:185], v[64:67]
	v_mfma_f32_16x16x32_bf16 v[116:119], v[198:201], v[162:165], v[116:119]
	v_mfma_f32_16x16x32_bf16 v[112:115], v[228:231], v[162:165], v[112:115]
	v_mfma_f32_16x16x32_bf16 v[100:103], v[198:201], v[170:173], v[100:103]
	v_mfma_f32_16x16x32_bf16 v[96:99], v[228:231], v[170:173], v[96:99]
	v_mfma_f32_16x16x32_bf16 v[84:87], v[198:201], v[178:181], v[84:87]
	v_mfma_f32_16x16x32_bf16 v[80:83], v[228:231], v[178:181], v[80:83]
	v_mfma_f32_16x16x32_bf16 v[68:71], v[198:201], v[186:189], v[68:71]
	v_mfma_f32_16x16x32_bf16 v[64:67], v[228:231], v[186:189], v[64:67]
	s_mov_b32 m0, s68
	v_lshl_add_u64 v[206:207], s[8:9], 0, v[140:141]
	s_barrier
	ds_read_b128 v[158:161], v151 offset:16384
	ds_read_b128 v[162:165], v151 offset:17408
	ds_read_b128 v[166:169], v151 offset:18432
	ds_read_b128 v[170:173], v151 offset:19456
	ds_read_b128 v[174:177], v151 offset:20480
	ds_read_b128 v[178:181], v151 offset:21504
	ds_read_b128 v[182:185], v151 offset:22528
	ds_read_b128 v[186:189], v151 offset:23552
	global_load_lds_dwordx4 v[206:207], off
	v_lshl_add_u64 v[208:209], s[8:9], 0, v[138:139]
	s_mov_b32 m0, s71
	s_nop 0
	global_load_lds_dwordx4 v[208:209], off
	s_barrier
	s_waitcnt lgkmcnt(0)
	v_mfma_f32_16x16x32_bf16 v[60:63], v[128:131], v[158:161], v[60:63]
	v_mfma_f32_16x16x32_bf16 v[56:59], v[146:149], v[158:161], v[56:59]
	v_mfma_f32_16x16x32_bf16 v[44:47], v[128:131], v[166:169], v[44:47]
	v_mfma_f32_16x16x32_bf16 v[40:43], v[146:149], v[166:169], v[40:43]
	v_mfma_f32_16x16x32_bf16 v[28:31], v[128:131], v[174:177], v[28:31]
	v_mfma_f32_16x16x32_bf16 v[24:27], v[146:149], v[174:177], v[24:27]
	v_mfma_f32_16x16x32_bf16 v[12:15], v[128:131], v[182:185], v[12:15]
	v_mfma_f32_16x16x32_bf16 v[8:11], v[146:149], v[182:185], v[8:11]
	v_mfma_f32_16x16x32_bf16 v[60:63], v[132:135], v[162:165], v[60:63]
	v_mfma_f32_16x16x32_bf16 v[56:59], v[154:157], v[162:165], v[56:59]
	v_mfma_f32_16x16x32_bf16 v[44:47], v[132:135], v[170:173], v[44:47]
	v_mfma_f32_16x16x32_bf16 v[40:43], v[154:157], v[170:173], v[40:43]
	v_mfma_f32_16x16x32_bf16 v[28:31], v[132:135], v[178:181], v[28:31]
	v_mfma_f32_16x16x32_bf16 v[24:27], v[154:157], v[178:181], v[24:27]
	v_mfma_f32_16x16x32_bf16 v[12:15], v[132:135], v[186:189], v[12:15]
	v_mfma_f32_16x16x32_bf16 v[8:11], v[154:157], v[186:189], v[8:11]
	s_barrier
; #define G_STAGE(bufoff, gbase) do { _Pragma("unroll") for (int _i = 0; _i < 2; ++_i) \
;     __builtin_amdgcn_global_load_lds((const unsigned*)((const char*)(gbase) + voffA[_i]), (LAS unsigned*)(lds + (bufoff) + ldsw + _i * 8192), 16, 0, 0); } while (0)
; #define G_LDA(dst, b, h) do { _Pragma("unroll") for (int m = 0; m < 4; ++m) _Pragma("unroll") for (int k = 0; k < 2; ++k) dst[m][k] = *(const LAS bf16x8*)(lds + G_SA(b, h) + aoff + m * 2048 + k * 1024); } while (0)
; #define G_LDB(dst, b, h) do { _Pragma("unroll") for (int n = 0; n < 2; ++n) _Pragma("unroll") for (int k = 0; k < 2; ++k) dst[n][k] = *(const LAS bf16x8*)(lds + G_SB(b, h) + boff + n * 2048 + k * 1024); } while (0)
; #define G_MMA(ai, bj, At, Bt) do { __builtin_amdgcn_s_setprio(1); _Pragma("unroll") for (int m = 0; m < 4; ++m) _Pragma("unroll") for (int n = 0; n < 2; ++n) _Pragma("unroll") for (int k = 0; k < 2; ++k) \
;     acc[ai][bj][m][n] = __builtin_amdgcn_mfma_f32_16x16x32_bf16(Bt[n][k], At[m][k], acc[ai][bj][m][n], 0, 0, 0); __builtin_amdgcn_s_setprio(0); } while (0)
; #define G_WAIT_V(n) asm volatile("s_waitcnt vmcnt(" #n ")" ::: "memory")
; #define G_WAIT_L(n) asm volatile("s_waitcnt lgkmcnt(" #n ")" ::: "memory")
; #define G_BAR __builtin_amdgcn_s_barrier()
; #define G_SCHED __builtin_amdgcn_sched_barrier(0)
; template <int MODE>
; __device__ __forceinline__ void gemm_phase(const Params& p, int layer, char* lds_generic) {
;     ...
;       G_STAGE(G_SB(0, 1), b2 + hstep);
;       G_WAIT_V(6); G_BAR; G_MMA(1, 1, At, B1); G_BAR;
;       G_LDB(B0, 1, 0); G_SCHED; G_LDA(At, 1, 0); G_STAGE(G_SA(0, 1), a2 + hstep);
;       G_WAIT_L(8); G_BAR; G_WAIT_L(0); G_MMA(0, 0, At, B0); G_BAR; G_SCHED;
;       G_LDB(B1, 1, 1); G_STAGE(G_SB(1, 0), b3);
;       G_BAR; G_WAIT_L(0); G_MMA(0, 1, At, B1); G_BAR;
;       G_LDA(At, 1, 1); G_STAGE(G_SA(1, 0), a3);
;       G_BAR; G_WAIT_L(0); G_MMA(1, 0, At, B0); G_BAR; G_SCHED;
	s_add_u32 s48, s6, 0x80000
	s_addc_u32 s49, s7, 0
	s_mov_b32 m0, s72
	v_lshl_add_u64 v[128:129], s[48:49], 0, v[140:141]
	global_load_lds_dwordx4 v[128:129], off
	v_lshl_add_u64 v[128:129], s[48:49], 0, v[138:139]
	s_mov_b32 m0, s73
	s_nop 0
	global_load_lds_dwordx4 v[128:129], off
	s_waitcnt vmcnt(6)
	s_barrier
	v_mfma_f32_16x16x32_bf16 v[52:55], v[194:197], v[158:161], v[52:55]
	v_mfma_f32_16x16x32_bf16 v[48:51], v[202:205], v[158:161], v[48:51]
	v_mfma_f32_16x16x32_bf16 v[36:39], v[194:197], v[166:169], v[36:39]
	v_mfma_f32_16x16x32_bf16 v[32:35], v[202:205], v[166:169], v[32:35]
	v_mfma_f32_16x16x32_bf16 v[20:23], v[194:197], v[174:177], v[20:23]
	v_mfma_f32_16x16x32_bf16 v[16:19], v[202:205], v[174:177], v[16:19]
	v_mfma_f32_16x16x32_bf16 v[4:7], v[194:197], v[182:185], v[4:7]
	v_mfma_f32_16x16x32_bf16 v[0:3], v[202:205], v[182:185], v[0:3]
	v_mfma_f32_16x16x32_bf16 v[52:55], v[198:201], v[162:165], v[52:55]
	v_mfma_f32_16x16x32_bf16 v[48:51], v[228:231], v[162:165], v[48:51]
	v_mfma_f32_16x16x32_bf16 v[36:39], v[198:201], v[170:173], v[36:39]
	v_mfma_f32_16x16x32_bf16 v[32:35], v[228:231], v[170:173], v[32:35]
	v_mfma_f32_16x16x32_bf16 v[20:23], v[198:201], v[178:181], v[20:23]
	v_mfma_f32_16x16x32_bf16 v[16:19], v[228:231], v[178:181], v[16:19]
	v_mfma_f32_16x16x32_bf16 v[4:7], v[198:201], v[186:189], v[4:7]
	v_mfma_f32_16x16x32_bf16 v[0:3], v[228:231], v[186:189], v[0:3]
	v_or_b32_e32 v128, 0x18000, v152
	v_add_u32_e32 v132, 0x18400, v152
	v_add_u32_e32 v146, 0x18800, v152
	v_add_u32_e32 v154, 0x18c00, v152
	s_barrier
	ds_read_b128 v[128:131], v128
	ds_read_b128 v[132:135], v132
	ds_read_b128 v[146:149], v146
	ds_read_b128 v[154:157], v154
	s_add_u32 s8, s8, 0x80000
	s_addc_u32 s9, s9, 0
	s_mov_b32 m0, s74
	v_lshl_add_u64 v[194:195], s[8:9], 0, v[140:141]
	ds_read_b128 v[158:161], v151 offset:32768
	ds_read_b128 v[162:165], v151 offset:33792
	ds_read_b128 v[166:169], v151 offset:34816
	ds_read_b128 v[170:173], v151 offset:35840
	ds_read_b128 v[174:177], v151 offset:36864
	ds_read_b128 v[178:181], v151 offset:37888
	ds_read_b128 v[182:185], v151 offset:38912
	ds_read_b128 v[186:189], v151 offset:39936
	global_load_lds_dwordx4 v[194:195], off
	v_lshl_add_u64 v[194:195], s[8:9], 0, v[138:139]
	s_mov_b32 m0, s75
	s_nop 0
	global_load_lds_dwordx4 v[194:195], off
	s_waitcnt lgkmcnt(8)
	s_barrier
	s_waitcnt lgkmcnt(0)
	v_mfma_f32_16x16x32_bf16 v[124:127], v[128:131], v[158:161], v[124:127]
	v_mfma_f32_16x16x32_bf16 v[120:123], v[146:149], v[158:161], v[120:123]
	v_mfma_f32_16x16x32_bf16 v[108:111], v[128:131], v[166:169], v[108:111]
	v_mfma_f32_16x16x32_bf16 v[104:107], v[146:149], v[166:169], v[104:107]
	v_mfma_f32_16x16x32_bf16 v[92:95], v[128:131], v[174:177], v[92:95]
	v_mfma_f32_16x16x32_bf16 v[88:91], v[146:149], v[174:177], v[88:91]
	v_mfma_f32_16x16x32_bf16 v[76:79], v[128:131], v[182:185], v[76:79]
	v_mfma_f32_16x16x32_bf16 v[72:75], v[146:149], v[182:185], v[72:75]
	v_mfma_f32_16x16x32_bf16 v[124:127], v[132:135], v[162:165], v[124:127]
	v_mfma_f32_16x16x32_bf16 v[120:123], v[154:157], v[162:165], v[120:123]
	v_mfma_f32_16x16x32_bf16 v[108:111], v[132:135], v[170:173], v[108:111]
	v_mfma_f32_16x16x32_bf16 v[104:107], v[154:157], v[170:173], v[104:107]
	v_mfma_f32_16x16x32_bf16 v[92:95], v[132:135], v[178:181], v[92:95]
	v_mfma_f32_16x16x32_bf16 v[88:91], v[154:157], v[178:181], v[88:91]
	v_mfma_f32_16x16x32_bf16 v[76:79], v[132:135], v[186:189], v[76:79]
	v_mfma_f32_16x16x32_bf16 v[72:75], v[154:157], v[186:189], v[72:75]
	s_barrier
	s_mov_b32 m0, s77
	v_or_b32_e32 v194, 0x1c000, v152
	v_add_u32_e32 v198, 0x1c400, v152
	v_add_u32_e32 v202, 0x1c800, v152
	v_lshl_add_u64 v[136:137], v[136:137], 0, s[90:91]
	ds_read_b128 v[194:197], v194
	ds_read_b128 v[198:201], v198
	v_add_u32_e32 v210, 0x1cc00, v152
	ds_read_b128 v[202:205], v202
	ds_read_b128 v[228:231], v210
	global_load_lds_dwordx4 v[136:137], off
	v_lshl_add_u64 v[136:137], v[190:191], 0, s[90:91]
	s_mov_b32 m0, s78
	s_nop 0
	global_load_lds_dwordx4 v[136:137], off
	s_barrier
	s_waitcnt lgkmcnt(0)
	v_mfma_f32_16x16x32_bf16 v[116:119], v[194:197], v[158:161], v[116:119]
	v_mfma_f32_16x16x32_bf16 v[112:115], v[202:205], v[158:161], v[112:115]
	v_mfma_f32_16x16x32_bf16 v[100:103], v[194:197], v[166:169], v[100:103]
	v_mfma_f32_16x16x32_bf16 v[96:99], v[202:205], v[166:169], v[96:99]
	v_mfma_f32_16x16x32_bf16 v[84:87], v[194:197], v[174:177], v[84:87]
	v_mfma_f32_16x16x32_bf16 v[80:83], v[202:205], v[174:177], v[80:83]
	v_mfma_f32_16x16x32_bf16 v[68:71], v[194:197], v[182:185], v[68:71]
	v_mfma_f32_16x16x32_bf16 v[64:67], v[202:205], v[182:185], v[64:67]
	v_mfma_f32_16x16x32_bf16 v[116:119], v[198:201], v[162:165], v[116:119]
	v_mfma_f32_16x16x32_bf16 v[112:115], v[228:231], v[162:165], v[112:115]
	v_mfma_f32_16x16x32_bf16 v[100:103], v[198:201], v[170:173], v[100:103]
	v_mfma_f32_16x16x32_bf16 v[96:99], v[228:231], v[170:173], v[96:99]
	v_mfma_f32_16x16x32_bf16 v[84:87], v[198:201], v[178:181], v[84:87]
	v_mfma_f32_16x16x32_bf16 v[80:83], v[228:231], v[178:181], v[80:83]
	v_mfma_f32_16x16x32_bf16 v[68:71], v[198:201], v[186:189], v[68:71]
	v_mfma_f32_16x16x32_bf16 v[64:67], v[228:231], v[186:189], v[64:67]
	s_mov_b32 m0, s79
	v_lshl_add_u64 v[136:137], v[206:207], 0, s[90:91]
	s_barrier
	ds_read_b128 v[158:161], v151 offset:49152
	ds_read_b128 v[162:165], v151 offset:50176
	ds_read_b128 v[166:169], v151 offset:51200
	ds_read_b128 v[170:173], v151 offset:52224
	ds_read_b128 v[174:177], v151 offset:53248
	ds_read_b128 v[178:181], v151 offset:54272
	ds_read_b128 v[182:185], v151 offset:55296
	ds_read_b128 v[186:189], v151 offset:56320
	global_load_lds_dwordx4 v[136:137], off
	v_lshl_add_u64 v[136:137], v[208:209], 0, s[90:91]
	s_mov_b32 m0, s86
	s_nop 0
	global_load_lds_dwordx4 v[136:137], off
	s_barrier
;   __device__ __forceinline__ bf16_t* Z() const { return (bf16_t*)(ws + 456 * MB); }
;   __device__ __forceinline__ float* cosT() const { return (float*)(ws + 904 * MB); }
;   __device__ __forceinline__ float* sinT() const { return (float*)(ws + 905 * MB); }
;   __device__ __forceinline__ float* RS() const { return (float*)(ws + 906 * MB); }
; #define G_STAGE(bufoff, gbase) do { _Pragma("unroll") for (int _i = 0; _i < 2; ++_i) \
;     __builtin_amdgcn_global_load_lds((const unsigned*)((const char*)(gbase) + voffA[_i]), (LAS unsigned*)(lds + (bufoff) + ldsw + _i * 8192), 16, 0, 0); } while (0)
; #define G_BAR __builtin_amdgcn_s_barrier()
; template <int MODE>
; __device__ __forceinline__ void gemm_epilogue(const Params& p, int layer, const f32x4 (&acc)[2][2][4][2], int pm, int pn, int wr, int wc, int fr, int fq) {
;     ...
;       const int row = pm * 256 + ai * 128 + wr * 64 + m * 16 + fr;
;       if (MODE == 0) {
;         const float rsv = p.RS()[row];
;         const int pos = (row < NPROMPT) ? (row & 8191) : (row & 4095);
; #pragma unroll
;         for (int bj = 0; bj < 2; ++bj) {
;           const int colt = pn * 256 + bj * 128 + wc * 32;
;           f32x4 v0 = acc[ai][bj][m][0] * rsv, v1 = acc[ai][bj][m][1] * rsv;
;           bf16_t* zp = p.Z() + (size_t)row * LDZ + colt;
;           if (colt < 2048) {
;             const int ti = pos * 32 + 16 * (wc & 1) + 4 * fq;
;             const f32x4 c = *(const f32x4*)(p.cosT() + ti), s = *(const f32x4*)(p.sinT() + ti);
;             const float qs = (colt < 1024) ? 0.18033688011112042f : 1.f;
;             const f32x4 o0 = (v0 * c - v1 * s) * qs, o1 = (v1 * c + v0 * s) * qs;
;             const u32x4 w = {cvtpk(o0[0], o0[1]), cvtpk(o0[2], o0[3]), cvtpk(o1[0], o1[1]), cvtpk(o1[2], o1[3])};
;             *(u32x4*)(zp + 8 * fq) = w;
;           } else {
;             if (colt >= 3072) {
; #pragma unroll
;               for (int e = 0; e < 4; ++e) { v0[e] = gelu_tanh(v0[e]); v1[e] = gelu_tanh(v1[e]); }
;             }
;             const u32x4 w = {cvtpk(v0[0], v0[1]), cvtpk(v0[2], v0[3]), cvtpk(v1[0], v1[1]), cvtpk(v1[2], v1[3])};
; template <int MODE>
; __device__ __forceinline__ void gemm_phase(const Params& p, int layer, char* lds_generic) {
;     ...
;       G_BAR; G_WAIT_L(0); G_MMA(1, 0, At, B0); G_BAR; G_SCHED;
;       G_STAGE(G_SB(1, 1), b3 + hstep);
;       G_WAIT_V(6); G_BAR; G_MMA(1, 1, At, B1); G_BAR;
	s_waitcnt lgkmcnt(0)
	v_mfma_f32_16x16x32_bf16 v[60:63], v[128:131], v[158:161], v[60:63]
	v_mfma_f32_16x16x32_bf16 v[56:59], v[146:149], v[158:161], v[56:59]
	v_mfma_f32_16x16x32_bf16 v[44:47], v[128:131], v[166:169], v[44:47]
	v_mfma_f32_16x16x32_bf16 v[40:43], v[146:149], v[166:169], v[40:43]
	v_mfma_f32_16x16x32_bf16 v[28:31], v[128:131], v[174:177], v[28:31]
	v_mfma_f32_16x16x32_bf16 v[24:27], v[146:149], v[174:177], v[24:27]
	v_mfma_f32_16x16x32_bf16 v[12:15], v[128:131], v[182:185], v[12:15]
	v_mfma_f32_16x16x32_bf16 v[8:11], v[146:149], v[182:185], v[8:11]
	v_mfma_f32_16x16x32_bf16 v[60:63], v[132:135], v[162:165], v[60:63]
	v_mfma_f32_16x16x32_bf16 v[56:59], v[154:157], v[162:165], v[56:59]
	v_mfma_f32_16x16x32_bf16 v[44:47], v[132:135], v[170:173], v[44:47]
	v_mfma_f32_16x16x32_bf16 v[40:43], v[154:157], v[170:173], v[40:43]
	v_mfma_f32_16x16x32_bf16 v[28:31], v[132:135], v[178:181], v[28:31]
	v_mfma_f32_16x16x32_bf16 v[24:27], v[154:157], v[178:181], v[24:27]
	v_mfma_f32_16x16x32_bf16 v[12:15], v[132:135], v[186:189], v[12:15]
	v_mfma_f32_16x16x32_bf16 v[8:11], v[154:157], v[186:189], v[8:11]
	s_barrier
	s_add_u32 s6, s6, 0x80080
	s_addc_u32 s7, s7, 0
	s_mov_b32 m0, s87
	v_lshl_add_u64 v[128:129], s[6:7], 0, v[140:141]
	global_load_lds_dwordx4 v[128:129], off
	v_lshl_add_u64 v[128:129], s[6:7], 0, v[138:139]
	s_mov_b32 m0, s88
	s_nop 0
	global_load_lds_dwordx4 v[128:129], off
	s_waitcnt vmcnt(6)
	s_barrier
	v_mfma_f32_16x16x32_bf16 v[52:55], v[194:197], v[158:161], v[52:55]
	v_mfma_f32_16x16x32_bf16 v[48:51], v[202:205], v[158:161], v[48:51]
	v_mfma_f32_16x16x32_bf16 v[36:39], v[194:197], v[166:169], v[36:39]
	v_mfma_f32_16x16x32_bf16 v[32:35], v[202:205], v[166:169], v[32:35]
	v_mfma_f32_16x16x32_bf16 v[20:23], v[194:197], v[174:177], v[20:23]
	v_mfma_f32_16x16x32_bf16 v[16:19], v[202:205], v[174:177], v[16:19]
	v_mfma_f32_16x16x32_bf16 v[4:7], v[194:197], v[182:185], v[4:7]
	v_mfma_f32_16x16x32_bf16 v[0:3], v[202:205], v[182:185], v[0:3]
	v_mfma_f32_16x16x32_bf16 v[52:55], v[198:201], v[162:165], v[52:55]
	v_mfma_f32_16x16x32_bf16 v[48:51], v[228:231], v[162:165], v[48:51]
	v_mfma_f32_16x16x32_bf16 v[36:39], v[198:201], v[170:173], v[36:39]
	v_mfma_f32_16x16x32_bf16 v[32:35], v[228:231], v[170:173], v[32:35]
	v_mfma_f32_16x16x32_bf16 v[20:23], v[198:201], v[178:181], v[20:23]
	v_mfma_f32_16x16x32_bf16 v[16:19], v[228:231], v[178:181], v[16:19]
	v_mfma_f32_16x16x32_bf16 v[4:7], v[198:201], v[186:189], v[4:7]
	v_mfma_f32_16x16x32_bf16 v[0:3], v[228:231], v[186:189], v[0:3]
	s_add_i32 s47, s47, 2
	s_add_u32 s4, s4, 0x100
	s_addc_u32 s5, s5, 0
	s_add_u32 s35, s35, 0x100
	s_addc_u32 s46, s46, 0
	s_cmp_gt_u32 s47, 29
	s_barrier
	s_cbranch_scc0 .LBB0_196
	v_lshl_add_u32 v146, s1, 8, v150
	v_ashrrev_i32_e32 v147, 31, v146
	v_lshl_add_u64 v[128:129], v[146:147], 2, s[12:13]
	global_load_dword v148, v[128:129], off
	global_load_dword v243, v[128:129], off offset:64
	global_load_dword v244, v[128:129], off offset:128
	global_load_dword v245, v[128:129], off offset:192
	global_load_dword v246, v[128:129], off offset:512
	global_load_dword v247, v[128:129], off offset:576
	global_load_dword v248, v[128:129], off offset:640
	global_load_dword v249, v[128:129], off offset:704
	s_lshl_b32 s1, s33, 8
	s_or_b32 s46, s1, s76
	s_cmpk_gt_i32 s46, 0x7ff
	s_movk_i32 s2, 0x4000
	s_cselect_b64 s[8:9], -1, 0
	v_cmp_gt_i32_e64 s[4:5], s2, v146
	s_mov_b64 s[6:7], -1
	s_and_b64 vcc, exec, s[8:9]
	s_waitcnt vmcnt(0)
	v_pk_mul_f32 v[126:127], v[126:127], v[148:149] op_sel_hi:[1,0]
	v_pk_mul_f32 v[124:125], v[124:125], v[148:149] op_sel_hi:[1,0]
	v_pk_mul_f32 v[122:123], v[122:123], v[148:149] op_sel_hi:[1,0]
	v_pk_mul_f32 v[120:121], v[120:121], v[148:149] op_sel_hi:[1,0]
	s_cbranch_vccz .LBB0_201
	v_mov_b64_e32 v[132:133], v[122:123]
	v_mov_b64_e32 v[136:137], v[126:127]
	s_cmpk_lt_u32 s1, 0xc00
	v_mov_b64_e32 v[130:131], v[120:121]
	v_mov_b64_e32 v[134:135], v[124:125]
	s_cbranch_scc1 .LBB0_200
	v_mul_f32_e32 v129, v120, v120
	v_fmamk_f32 v129, v129, 0x3dd2d3e8, v214
	v_mul_f32_e32 v130, v125, v125
	v_mul_f32_e64 v129, v120, -v129
	v_fmamk_f32 v130, v130, 0x3dd2d3e8, v214
	v_exp_f32_e32 v129, v129
	v_mul_f32_e64 v130, v125, -v130
	v_exp_f32_e32 v131, v130
	v_mul_f32_e32 v133, v122, v122
	v_add_f32_e32 v129, 1.0, v129
	v_mul_f32_e32 v128, v124, v124
	v_rcp_f32_e32 v130, v129
	v_add_f32_e32 v129, 1.0, v131
	v_mul_f32_e32 v131, v121, v121
	v_mul_f32_e32 v132, v126, v126
	v_fmamk_f32 v133, v133, 0x3dd2d3e8, v214
	v_mul_f32_e32 v134, v127, v127
	v_mul_f32_e32 v135, v123, v123
	v_fmamk_f32 v128, v128, 0x3dd2d3e8, v214
	v_fmamk_f32 v131, v131, 0x3dd2d3e8, v214
	v_fmamk_f32 v132, v132, 0x3dd2d3e8, v214
	v_mul_f32_e64 v133, v122, -v133
	v_fmamk_f32 v134, v134, 0x3dd2d3e8, v214
	v_fmamk_f32 v135, v135, 0x3dd2d3e8, v214
	v_mul_f32_e64 v128, v124, -v128
	v_mul_f32_e64 v131, v121, -v131
	v_mul_f32_e64 v132, v126, -v132
	v_exp_f32_e32 v133, v133
	v_mul_f32_e64 v134, v127, -v134
	v_mul_f32_e64 v135, v123, -v135
	v_exp_f32_e32 v128, v128
	v_exp_f32_e32 v131, v131
	v_exp_f32_e32 v132, v132
	v_exp_f32_e32 v134, v134
	v_exp_f32_e32 v135, v135
	v_add_f32_e32 v133, 1.0, v133
	v_add_f32_e32 v128, 1.0, v128
	v_add_f32_e32 v131, 1.0, v131
	v_add_f32_e32 v132, 1.0, v132
	v_rcp_f32_e32 v154, v133
	v_add_f32_e32 v133, 1.0, v134
	v_add_f32_e32 v134, 1.0, v135
	v_rcp_f32_e32 v128, v128
	v_rcp_f32_e32 v129, v129
	v_rcp_f32_e32 v132, v132
	v_rcp_f32_e32 v133, v133
	v_rcp_f32_e32 v155, v134
	v_rcp_f32_e32 v131, v131
	v_pk_mul_f32 v[134:135], v[124:125], v[128:129]
	v_pk_mul_f32 v[136:137], v[126:127], v[132:133]
	v_pk_mul_f32 v[132:133], v[122:123], v[154:155]
	v_pk_mul_f32 v[130:131], v[120:121], v[130:131]
